# attention loop v3: 3-slot LDS ring, one barrier per tile (waves 0-3 sync at tile end, waves 4-7 after QK), scalar-base K/V loads
# speedup vs baseline: 1.0720x; 1.0077x over previous
.LBB0_28:
	s_waitcnt vmcnt(21)
	v_lshlrev_b32_e32 v51, 16, v46
	v_and_b32_e32 v46, 0xffff0000, v46
	s_waitcnt vmcnt(6)
	v_mul_f32_e32 v51, v50, v51
	v_mul_f32_e32 v46, v50, v46
	v_cvt_pk_bf16_f32 v126, v51, v46
	v_lshlrev_b32_e32 v46, 16, v47
	v_and_b32_e32 v47, 0xffff0000, v47
	v_mul_f32_e32 v46, v50, v46
	v_mul_f32_e32 v47, v50, v47
	v_cvt_pk_bf16_f32 v127, v46, v47
	v_lshlrev_b32_e32 v46, 16, v48
	v_and_b32_e32 v47, 0xffff0000, v48
	v_mul_f32_e32 v46, v50, v46
	v_mul_f32_e32 v47, v50, v47
	v_cvt_pk_bf16_f32 v128, v46, v47
	v_lshlrev_b32_e32 v46, 16, v49
	v_and_b32_e32 v47, 0xffff0000, v49
	v_mul_f32_e32 v46, v50, v46
	v_mul_f32_e32 v47, v50, v47
	v_cvt_pk_bf16_f32 v129, v46, v47
	v_lshlrev_b32_e32 v46, 16, v42
	v_and_b32_e32 v42, 0xffff0000, v42
	v_mul_f32_e32 v46, v50, v46
	v_mul_f32_e32 v42, v50, v42
	v_cvt_pk_bf16_f32 v142, v46, v42
	v_lshlrev_b32_e32 v42, 16, v43
	v_and_b32_e32 v43, 0xffff0000, v43
	v_mul_f32_e32 v42, v50, v42
	v_mul_f32_e32 v43, v50, v43
	v_cvt_pk_bf16_f32 v143, v42, v43
	v_lshlrev_b32_e32 v42, 16, v44
	v_and_b32_e32 v43, 0xffff0000, v44
	v_mul_f32_e32 v42, v50, v42
	v_mul_f32_e32 v43, v50, v43
	v_cvt_pk_bf16_f32 v144, v42, v43
	v_lshlrev_b32_e32 v42, 16, v45
	v_and_b32_e32 v43, 0xffff0000, v45
	v_mul_f32_e32 v42, v50, v42
	v_mul_f32_e32 v43, v50, v43
	v_cvt_pk_bf16_f32 v145, v42, v43
	v_lshlrev_b32_e32 v42, 16, v38
	v_and_b32_e32 v38, 0xffff0000, v38
	v_mul_f32_e32 v42, v50, v42
	v_mul_f32_e32 v38, v50, v38
	v_cvt_pk_bf16_f32 v146, v42, v38
	v_lshlrev_b32_e32 v38, 16, v39
	v_and_b32_e32 v39, 0xffff0000, v39
	v_mul_f32_e32 v38, v50, v38
	v_mul_f32_e32 v39, v50, v39
	v_cvt_pk_bf16_f32 v147, v38, v39
	v_lshlrev_b32_e32 v38, 16, v40
	v_and_b32_e32 v39, 0xffff0000, v40
	v_mul_f32_e32 v38, v50, v38
	v_mul_f32_e32 v39, v50, v39
	v_cvt_pk_bf16_f32 v148, v38, v39
	v_lshlrev_b32_e32 v38, 16, v41
	v_and_b32_e32 v39, 0xffff0000, v41
	v_mul_f32_e32 v38, v50, v38
	v_mul_f32_e32 v39, v50, v39
	v_cvt_pk_bf16_f32 v149, v38, v39
	v_lshlrev_b32_e32 v38, 16, v34
	v_and_b32_e32 v34, 0xffff0000, v34
	v_mul_f32_e32 v38, v50, v38
	v_mul_f32_e32 v34, v50, v34
	v_cvt_pk_bf16_f32 v150, v38, v34
	v_lshlrev_b32_e32 v34, 16, v35
	v_and_b32_e32 v35, 0xffff0000, v35
	v_mul_f32_e32 v34, v50, v34
	v_mul_f32_e32 v35, v50, v35
	v_cvt_pk_bf16_f32 v151, v34, v35
	v_lshlrev_b32_e32 v34, 16, v36
	v_and_b32_e32 v35, 0xffff0000, v36
	v_mul_f32_e32 v34, v50, v34
	v_mul_f32_e32 v35, v50, v35
	v_cvt_pk_bf16_f32 v152, v34, v35
	v_lshlrev_b32_e32 v34, 16, v37
	v_and_b32_e32 v35, 0xffff0000, v37
	v_mul_f32_e32 v34, v50, v34
	v_mul_f32_e32 v35, v50, v35
	v_cvt_pk_bf16_f32 v153, v34, v35
	v_lshlrev_b32_e32 v34, 16, v30
	v_and_b32_e32 v30, 0xffff0000, v30
	v_mul_f32_e32 v34, v50, v34
	v_mul_f32_e32 v30, v50, v30
	v_cvt_pk_bf16_f32 v154, v34, v30
	v_lshlrev_b32_e32 v30, 16, v31
	v_and_b32_e32 v31, 0xffff0000, v31
	v_mul_f32_e32 v30, v50, v30
	v_mul_f32_e32 v31, v50, v31
	v_cvt_pk_bf16_f32 v155, v30, v31
	v_lshlrev_b32_e32 v30, 16, v32
	v_and_b32_e32 v31, 0xffff0000, v32
	v_mul_f32_e32 v30, v50, v30
	v_mul_f32_e32 v31, v50, v31
	v_cvt_pk_bf16_f32 v156, v30, v31
	v_lshlrev_b32_e32 v30, 16, v33
	v_and_b32_e32 v31, 0xffff0000, v33
	v_mul_f32_e32 v30, v50, v30
	v_mul_f32_e32 v31, v50, v31
	v_cvt_pk_bf16_f32 v157, v30, v31
	v_lshlrev_b32_e32 v30, 16, v26
	v_and_b32_e32 v26, 0xffff0000, v26
	v_mul_f32_e32 v30, v50, v30
	v_mul_f32_e32 v26, v50, v26
	v_cvt_pk_bf16_f32 v158, v30, v26
	v_lshlrev_b32_e32 v26, 16, v27
	v_and_b32_e32 v27, 0xffff0000, v27
	v_mul_f32_e32 v26, v50, v26
	v_mul_f32_e32 v27, v50, v27
	v_cvt_pk_bf16_f32 v159, v26, v27
	v_lshlrev_b32_e32 v26, 16, v28
	v_and_b32_e32 v27, 0xffff0000, v28
	v_mul_f32_e32 v26, v50, v26
	v_mul_f32_e32 v27, v50, v27
	v_cvt_pk_bf16_f32 v160, v26, v27
	v_lshlrev_b32_e32 v26, 16, v29
	v_and_b32_e32 v27, 0xffff0000, v29
	v_mul_f32_e32 v26, v50, v26
	v_mul_f32_e32 v27, v50, v27
	v_cvt_pk_bf16_f32 v161, v26, v27
	v_lshlrev_b32_e32 v26, 16, v22
	v_and_b32_e32 v22, 0xffff0000, v22
	v_mul_f32_e32 v26, v50, v26
	v_mul_f32_e32 v22, v50, v22
	v_cvt_pk_bf16_f32 v162, v26, v22
	v_lshlrev_b32_e32 v22, 16, v23
	v_and_b32_e32 v23, 0xffff0000, v23
	v_mul_f32_e32 v22, v50, v22
	v_mul_f32_e32 v23, v50, v23
	v_cvt_pk_bf16_f32 v163, v22, v23
	v_lshlrev_b32_e32 v22, 16, v24
	v_and_b32_e32 v23, 0xffff0000, v24
	v_mul_f32_e32 v22, v50, v22
	v_mul_f32_e32 v23, v50, v23
	v_cvt_pk_bf16_f32 v164, v22, v23
	v_lshlrev_b32_e32 v22, 16, v25
	v_and_b32_e32 v23, 0xffff0000, v25
	v_mul_f32_e32 v22, v50, v22
	v_mul_f32_e32 v23, v50, v23
	v_cvt_pk_bf16_f32 v165, v22, v23
	v_lshlrev_b32_e32 v22, 16, v18
	v_and_b32_e32 v18, 0xffff0000, v18
	v_mul_f32_e32 v22, v50, v22
	v_mul_f32_e32 v18, v50, v18
	v_cvt_pk_bf16_f32 v166, v22, v18
	v_lshlrev_b32_e32 v18, 16, v19
	v_and_b32_e32 v19, 0xffff0000, v19
	v_mul_f32_e32 v18, v50, v18
	v_mul_f32_e32 v19, v50, v19
	v_cvt_pk_bf16_f32 v167, v18, v19
	v_lshlrev_b32_e32 v18, 16, v20
	v_and_b32_e32 v19, 0xffff0000, v20
	v_mul_f32_e32 v18, v50, v18
	v_mul_f32_e32 v19, v50, v19
	v_cvt_pk_bf16_f32 v168, v18, v19
	v_lshlrev_b32_e32 v18, 16, v21
	v_and_b32_e32 v19, 0xffff0000, v21
	v_mul_f32_e32 v18, v50, v18
	v_mul_f32_e32 v19, v50, v19
	v_cvt_pk_bf16_f32 v169, v18, v19
	v_lshlrev_b32_e32 v18, 16, v14
	v_and_b32_e32 v14, 0xffff0000, v14
	v_mul_f32_e32 v18, v50, v18
	v_mul_f32_e32 v14, v50, v14
	v_cvt_pk_bf16_f32 v170, v18, v14
	v_lshlrev_b32_e32 v14, 16, v15
	v_and_b32_e32 v15, 0xffff0000, v15
	v_mul_f32_e32 v14, v50, v14
	v_mul_f32_e32 v15, v50, v15
	v_cvt_pk_bf16_f32 v171, v14, v15
	v_lshlrev_b32_e32 v14, 16, v16
	v_and_b32_e32 v15, 0xffff0000, v16
	v_mul_f32_e32 v14, v50, v14
	v_mul_f32_e32 v15, v50, v15
	v_cvt_pk_bf16_f32 v172, v14, v15
	v_lshlrev_b32_e32 v14, 16, v17
	v_and_b32_e32 v15, 0xffff0000, v17
	v_mul_f32_e32 v14, v50, v14
	v_mul_f32_e32 v15, v50, v15
	v_cvt_pk_bf16_f32 v173, v14, v15
	v_lshlrev_b32_e32 v14, 16, v10
	v_and_b32_e32 v10, 0xffff0000, v10
	v_mul_f32_e32 v14, v50, v14
	v_mul_f32_e32 v10, v50, v10
	v_cvt_pk_bf16_f32 v174, v14, v10
	v_lshlrev_b32_e32 v10, 16, v11
	v_and_b32_e32 v11, 0xffff0000, v11
	v_mul_f32_e32 v10, v50, v10
	v_mul_f32_e32 v11, v50, v11
	v_cvt_pk_bf16_f32 v175, v10, v11
	v_lshlrev_b32_e32 v10, 16, v12
	v_and_b32_e32 v11, 0xffff0000, v12
	v_mul_f32_e32 v10, v50, v10
	v_mul_f32_e32 v11, v50, v11
	v_cvt_pk_bf16_f32 v176, v10, v11
	v_lshlrev_b32_e32 v10, 16, v13
	v_and_b32_e32 v11, 0xffff0000, v13
	v_mul_f32_e32 v10, v50, v10
	v_mul_f32_e32 v11, v50, v11
	v_cvt_pk_bf16_f32 v177, v10, v11
	v_lshlrev_b32_e32 v10, 16, v6
	v_and_b32_e32 v6, 0xffff0000, v6
	v_mul_f32_e32 v10, v50, v10
	v_mul_f32_e32 v6, v50, v6
	v_cvt_pk_bf16_f32 v178, v10, v6
	v_lshlrev_b32_e32 v6, 16, v7
	v_and_b32_e32 v7, 0xffff0000, v7
	v_mul_f32_e32 v6, v50, v6
	v_mul_f32_e32 v7, v50, v7
	v_cvt_pk_bf16_f32 v179, v6, v7
	v_lshlrev_b32_e32 v6, 16, v8
	v_and_b32_e32 v7, 0xffff0000, v8
	v_mul_f32_e32 v6, v50, v6
	v_mul_f32_e32 v7, v50, v7
	v_cvt_pk_bf16_f32 v180, v6, v7
	v_lshlrev_b32_e32 v6, 16, v9
	v_and_b32_e32 v7, 0xffff0000, v9
	v_mul_f32_e32 v6, v50, v6
	v_mul_f32_e32 v7, v50, v7
	v_cvt_pk_bf16_f32 v181, v6, v7
	v_lshlrev_b32_e32 v6, 16, v2
	v_and_b32_e32 v2, 0xffff0000, v2
	v_mul_f32_e32 v6, v50, v6
	v_mul_f32_e32 v2, v50, v2
	v_cvt_pk_bf16_f32 v182, v6, v2
	v_lshlrev_b32_e32 v2, 16, v3
	v_and_b32_e32 v3, 0xffff0000, v3
	v_mul_f32_e32 v2, v50, v2
	v_mul_f32_e32 v3, v50, v3
	v_cvt_pk_bf16_f32 v183, v2, v3
	v_lshlrev_b32_e32 v2, 16, v4
	v_and_b32_e32 v3, 0xffff0000, v4
	v_mul_f32_e32 v2, v50, v2
	v_mul_f32_e32 v3, v50, v3
	v_cvt_pk_bf16_f32 v184, v2, v3
	v_lshlrev_b32_e32 v2, 16, v5
	v_and_b32_e32 v3, 0xffff0000, v5
	v_mul_f32_e32 v2, v50, v2
	v_mul_f32_e32 v3, v50, v3
	v_cvt_pk_bf16_f32 v185, v2, v3
	v_lshl_add_u64 v[2:3], s[20:21], 0, v[198:199]
	s_mov_b64 s[14:15], 0x1c000
	v_lshl_add_u64 v[206:207], v[2:3], 0, s[14:15]
	v_mov_b64_e32 v[2:3], s[42:43]
	v_mov_b32_e32 v16, v1
	v_mov_b32_e32 v17, v1
	v_mad_i64_i32 v[208:209], s[14:15], v200, s11, v[2:3]
	v_mov_b32_e32 v2, v1
	v_mov_b32_e32 v3, v1
	v_mov_b32_e32 v4, v1
	v_mov_b32_e32 v5, v1
	v_mov_b32_e32 v6, v1
	v_mov_b32_e32 v7, v1
	v_mov_b32_e32 v8, v1
	v_mov_b32_e32 v9, v1
	v_mov_b32_e32 v10, v1
	v_mov_b32_e32 v11, v1
	v_mov_b32_e32 v12, v1
	v_mov_b32_e32 v13, v1
	v_mov_b32_e32 v14, v1
	v_mov_b32_e32 v15, v1
	v_mov_b64_e32 v[32:33], v[16:17]
	v_mov_b64_e32 v[48:49], v[16:17]
	v_mov_b64_e32 v[64:65], v[16:17]
	s_lshr_b32 s5, s11, 6
	v_mov_b32_e32 v224, 0
	v_mov_b32_e32 v223, 0xf149f2ca
	s_mov_b32 s11, 4
	v_mov_b64_e32 v[30:31], v[14:15]
	v_mov_b64_e32 v[28:29], v[12:13]
	v_mov_b64_e32 v[26:27], v[10:11]
	v_mov_b64_e32 v[24:25], v[8:9]
	v_mov_b64_e32 v[22:23], v[6:7]
	v_mov_b64_e32 v[20:21], v[4:5]
	v_mov_b64_e32 v[18:19], v[2:3]
	v_mov_b64_e32 v[46:47], v[14:15]
	v_mov_b64_e32 v[44:45], v[12:13]
	v_mov_b64_e32 v[42:43], v[10:11]
	v_mov_b64_e32 v[40:41], v[8:9]
	v_mov_b64_e32 v[38:39], v[6:7]
	v_mov_b64_e32 v[36:37], v[4:5]
	v_mov_b64_e32 v[34:35], v[2:3]
	v_mov_b64_e32 v[62:63], v[14:15]
	v_mov_b64_e32 v[60:61], v[12:13]
	v_mov_b64_e32 v[58:59], v[10:11]
	v_mov_b64_e32 v[56:57], v[8:9]
	v_mov_b64_e32 v[54:55], v[6:7]
	v_mov_b64_e32 v[52:53], v[4:5]
	v_mov_b64_e32 v[50:51], v[2:3]
	v_readlane_b32 s33, v254, 35
	s_mov_b32 s34, 0x18000
	s_waitcnt vmcnt(5)
	v_lshlrev_b32_e32 v204, 1, v190
	s_lshl_b32 s13, s5, 7
	v_mul_lo_u32 v207, v188, s13
	v_add_u32_e32 v207, v207, v194
	s_add_u32 s66, s20, 0x12000
	s_addc_u32 s67, s21, 0
	s_add_u32 s74, s20, 0x14000
	s_addc_u32 s75, s21, 0
	s_add_u32 s76, s20, 0x16000
	s_addc_u32 s77, s21, 0
	s_add_u32 s68, s42, 0x180
	s_addc_u32 s69, s43, 0
	s_lshl_b32 s13, s5, 13
	s_add_u32 s78, s68, s13
	s_addc_u32 s79, s69, 0
	s_mov_b32 s70, 0
	s_mov_b32 s71, 44032
	s_mov_b32 s72, 44032
	s_mov_b32 s11, -1
	s_add_i32 s13, s11, 2
	s_cmp_ge_u32 s13, s5
	s_cbranch_scc1 .Latt3_wskip_1
	v_add_u32_e32 v206, s72, v219
	v_add_u32_e32 v208, s72, v220
	v_add_u32_e32 v186, s72, v221
	v_add_u32_e32 v187, s72, v222
	s_add_i32 s13, s11, 3
	s_cmp_ge_u32 s13, s5
	s_cbranch_scc1 .Latt3_wtail_2
	s_waitcnt vmcnt(9)
	ds_write_b128 v206, v[102:105]
	s_waitcnt vmcnt(8)
	ds_write_b128 v208, v[106:109]
	s_waitcnt vmcnt(7)
	ds_write_b128 v186, v[114:117]
	s_waitcnt vmcnt(6)
	ds_write_b128 v187, v[98:101] offset:25600
	s_waitcnt vmcnt(5)
	ds_write_b128 v187, v[110:113] offset:34816
	s_branch .Latt3_wld_3
.Latt3_wtail_2:
	s_waitcnt vmcnt(4)
	ds_write_b128 v206, v[102:105]
	s_waitcnt vmcnt(3)
	ds_write_b128 v208, v[106:109]
	s_waitcnt vmcnt(2)
	ds_write_b128 v186, v[114:117]
	s_waitcnt vmcnt(1)
	ds_write_b128 v187, v[98:101] offset:25600
	s_waitcnt vmcnt(0)
	ds_write_b128 v187, v[110:113] offset:34816
.Latt3_wld_3:
	s_add_i32 s13, s11, 4
	s_cmp_ge_u32 s13, s5
	s_cbranch_scc1 .Latt3_wdone_4
	global_load_dwordx4 v[102:105], v204, s[66:67]
	global_load_dwordx4 v[106:109], v204, s[74:75]
	global_load_dwordx4 v[114:117], v204, s[76:77]
	global_load_dwordx4 v[98:101], v207, s[68:69]
	global_load_dwordx4 v[110:113], v207, s[78:79]
	s_add_u32 s66, s66, 0x6000
	s_addc_u32 s67, s67, 0
	s_add_u32 s74, s74, 0x6000
	s_addc_u32 s75, s75, 0
	s_add_u32 s76, s76, 0x6000
	s_addc_u32 s77, s77, 0
	s_add_u32 s68, s68, 0x80
	s_addc_u32 s69, s69, 0
	s_add_u32 s78, s78, 0x80
	s_addc_u32 s79, s79, 0
.Latt3_wdone_4:
.Latt3_wskip_1:
	s_mov_b32 s72, 88064
	s_mov_b32 s11, 0
	s_waitcnt lgkmcnt(0)
	s_barrier
	s_andn2_b64 vcc, exec, s[38:39]
	s_cbranch_vccnz .Latt3_A_loop
	s_branch .Latt3_B_loop
.Latt3_A_loop:
	v_add_u32_e32 v209, s70, v215
	v_add_u32_e32 v205, s70, v216
	ds_read_b128 v[226:229], v209
	ds_read_b128 v[236:239], v209 offset:12800
	ds_read_b128 v[240:243], v209 offset:32
	ds_read_b128 v[244:247], v209 offset:12832
	ds_read_b128 v[248:251], v209 offset:64
	ds_read_b128 v[210:213], v209 offset:12864
	s_waitcnt lgkmcnt(5)
	v_mfma_f32_32x32x16_bf16 v[82:97], v[226:229], v[126:129], 0
	ds_read_b128 v[226:229], v209 offset:96
	s_waitcnt lgkmcnt(5)
	v_mfma_f32_32x32x16_bf16 v[66:81], v[236:239], v[126:129], 0
	ds_read_b128 v[236:239], v209 offset:12896
	s_waitcnt lgkmcnt(5)
	v_mfma_f32_32x32x16_bf16 v[82:97], v[240:243], v[142:145], v[82:97]
	ds_read_b128 v[240:243], v209 offset:128
	s_waitcnt lgkmcnt(5)
	v_mfma_f32_32x32x16_bf16 v[66:81], v[244:247], v[142:145], v[66:81]
	ds_read_b128 v[244:247], v209 offset:12928
	s_waitcnt lgkmcnt(5)
	v_mfma_f32_32x32x16_bf16 v[82:97], v[248:251], v[146:149], v[82:97]
	ds_read_b128 v[248:251], v209 offset:160
	s_waitcnt lgkmcnt(5)
	v_mfma_f32_32x32x16_bf16 v[66:81], v[210:213], v[146:149], v[66:81]
	ds_read_b128 v[210:213], v209 offset:12960
	s_waitcnt lgkmcnt(5)
	v_mfma_f32_32x32x16_bf16 v[82:97], v[226:229], v[150:153], v[82:97]
	ds_read_b128 v[226:229], v209 offset:192
	s_waitcnt lgkmcnt(5)
	v_mfma_f32_32x32x16_bf16 v[66:81], v[236:239], v[150:153], v[66:81]
	ds_read_b128 v[236:239], v209 offset:12992
	s_waitcnt lgkmcnt(5)
	v_mfma_f32_32x32x16_bf16 v[82:97], v[240:243], v[154:157], v[82:97]
	ds_read_b128 v[240:243], v209 offset:224
	s_waitcnt lgkmcnt(5)
	v_mfma_f32_32x32x16_bf16 v[66:81], v[244:247], v[154:157], v[66:81]
	ds_read_b128 v[244:247], v209 offset:13024
	s_waitcnt lgkmcnt(5)
	v_mfma_f32_32x32x16_bf16 v[82:97], v[248:251], v[158:161], v[82:97]
	ds_read_b128 v[248:251], v209 offset:256
	s_waitcnt lgkmcnt(5)
	v_mfma_f32_32x32x16_bf16 v[66:81], v[210:213], v[158:161], v[66:81]
	ds_read_b128 v[210:213], v209 offset:13056
	s_waitcnt lgkmcnt(5)
	v_mfma_f32_32x32x16_bf16 v[82:97], v[226:229], v[162:165], v[82:97]
	ds_read_b128 v[226:229], v209 offset:288
	s_waitcnt lgkmcnt(5)
	v_mfma_f32_32x32x16_bf16 v[66:81], v[236:239], v[162:165], v[66:81]
	ds_read_b128 v[236:239], v209 offset:13088
	s_waitcnt lgkmcnt(5)
	v_mfma_f32_32x32x16_bf16 v[82:97], v[240:243], v[166:169], v[82:97]
	ds_read_b128 v[240:243], v209 offset:320
	s_waitcnt lgkmcnt(5)
	v_mfma_f32_32x32x16_bf16 v[66:81], v[244:247], v[166:169], v[66:81]
	ds_read_b128 v[244:247], v209 offset:13120
	s_waitcnt lgkmcnt(5)
	v_mfma_f32_32x32x16_bf16 v[82:97], v[248:251], v[170:173], v[82:97]
	ds_read_b128 v[248:251], v209 offset:352
	s_waitcnt lgkmcnt(5)
	v_mfma_f32_32x32x16_bf16 v[66:81], v[210:213], v[170:173], v[66:81]
	ds_read_b128 v[210:213], v209 offset:13152
	s_waitcnt lgkmcnt(5)
	v_mfma_f32_32x32x16_bf16 v[82:97], v[226:229], v[174:177], v[82:97]
	s_waitcnt lgkmcnt(4)
	v_mfma_f32_32x32x16_bf16 v[66:81], v[236:239], v[174:177], v[66:81]
	s_waitcnt lgkmcnt(3)
	v_mfma_f32_32x32x16_bf16 v[82:97], v[240:243], v[178:181], v[82:97]
	s_waitcnt lgkmcnt(2)
	v_mfma_f32_32x32x16_bf16 v[66:81], v[244:247], v[178:181], v[66:81]
	s_waitcnt lgkmcnt(1)
	v_mfma_f32_32x32x16_bf16 v[82:97], v[248:251], v[182:185], v[82:97]
	s_waitcnt lgkmcnt(0)
	v_mfma_f32_32x32x16_bf16 v[66:81], v[210:213], v[182:185], v[66:81]
	s_setprio 2
	ds_read_b128 v[236:239], v205 offset:25600
	ds_read_b128 v[240:243], v205 offset:30208
	ds_read_b128 v[244:247], v205 offset:34816
	ds_read_b128 v[248:251], v205 offset:39424
	ds_read_b128 v[210:213], v205 offset:25632
	s_nop 4
	v_max_f32_e32 v186, v83, v83
	v_max_f32_e32 v187, v82, v82
	v_max_f32_e32 v186, v187, v186
	v_max3_f32 v186, v186, v84, v85
	v_max3_f32 v186, v186, v86, v87
	v_max3_f32 v186, v186, v88, v89
	v_max3_f32 v186, v186, v90, v91
	v_max3_f32 v186, v186, v92, v93
	v_max3_f32 v186, v186, v94, v95
	v_max3_f32 v186, v186, v96, v97
	v_max3_f32 v186, v186, v66, v67
	v_max3_f32 v186, v186, v68, v69
	v_max3_f32 v186, v186, v70, v71
	v_max3_f32 v186, v186, v72, v73
	v_max3_f32 v186, v186, v74, v75
	v_max3_f32 v186, v186, v76, v77
	v_max3_f32 v186, v186, v78, v79
	v_max3_f32 v186, v186, v80, v81
	ds_bpermute_b32 v187, v214, v186
	s_waitcnt lgkmcnt(0)
	v_max_f32_e32 v187, v187, v187
	v_max_f32_e32 v187, v186, v187
	v_add_f32_e32 v186, 0x41380000, v223
	v_cmp_gt_f32_e32 vcc, v187, v186
	s_cbranch_vccz .Latt3_nr_5
	v_max_f32_e32 v186, v187, v187
	v_max_f32_e32 v187, v223, v223
	v_max_f32_e32 v187, v187, v186
	v_sub_f32_e32 v186, v223, v187
	v_exp_f32_e32 v186, v186
	v_mov_b32_e32 v223, v187
	v_pk_mul_f32 v[64:65], v[64:65], v[186:187] op_sel_hi:[1,0]
	v_pk_mul_f32 v[62:63], v[62:63], v[186:187] op_sel_hi:[1,0]
	v_pk_mul_f32 v[60:61], v[60:61], v[186:187] op_sel_hi:[1,0]
	v_pk_mul_f32 v[58:59], v[58:59], v[186:187] op_sel_hi:[1,0]
	v_pk_mul_f32 v[56:57], v[56:57], v[186:187] op_sel_hi:[1,0]
	v_pk_mul_f32 v[54:55], v[54:55], v[186:187] op_sel_hi:[1,0]
	v_pk_mul_f32 v[52:53], v[52:53], v[186:187] op_sel_hi:[1,0]
	v_pk_mul_f32 v[50:51], v[50:51], v[186:187] op_sel_hi:[1,0]
	v_pk_mul_f32 v[48:49], v[48:49], v[186:187] op_sel_hi:[1,0]
	v_pk_mul_f32 v[46:47], v[46:47], v[186:187] op_sel_hi:[1,0]
	v_pk_mul_f32 v[44:45], v[44:45], v[186:187] op_sel_hi:[1,0]
	v_pk_mul_f32 v[42:43], v[42:43], v[186:187] op_sel_hi:[1,0]
	v_pk_mul_f32 v[40:41], v[40:41], v[186:187] op_sel_hi:[1,0]
	v_pk_mul_f32 v[38:39], v[38:39], v[186:187] op_sel_hi:[1,0]
	v_pk_mul_f32 v[36:37], v[36:37], v[186:187] op_sel_hi:[1,0]
	v_pk_mul_f32 v[34:35], v[34:35], v[186:187] op_sel_hi:[1,0]
	v_pk_mul_f32 v[32:33], v[32:33], v[186:187] op_sel_hi:[1,0]
	v_pk_mul_f32 v[30:31], v[30:31], v[186:187] op_sel_hi:[1,0]
	v_pk_mul_f32 v[28:29], v[28:29], v[186:187] op_sel_hi:[1,0]
	v_pk_mul_f32 v[26:27], v[26:27], v[186:187] op_sel_hi:[1,0]
	v_pk_mul_f32 v[24:25], v[24:25], v[186:187] op_sel_hi:[1,0]
	v_pk_mul_f32 v[22:23], v[22:23], v[186:187] op_sel_hi:[1,0]
	v_pk_mul_f32 v[20:21], v[20:21], v[186:187] op_sel_hi:[1,0]
	v_pk_mul_f32 v[18:19], v[18:19], v[186:187] op_sel_hi:[1,0]
	v_pk_mul_f32 v[16:17], v[16:17], v[186:187] op_sel_hi:[1,0]
	v_pk_mul_f32 v[14:15], v[14:15], v[186:187] op_sel_hi:[1,0]
	v_pk_mul_f32 v[12:13], v[12:13], v[186:187] op_sel_hi:[1,0]
	v_pk_mul_f32 v[10:11], v[10:11], v[186:187] op_sel_hi:[1,0]
	v_pk_mul_f32 v[8:9], v[8:9], v[186:187] op_sel_hi:[1,0]
	v_pk_mul_f32 v[6:7], v[6:7], v[186:187] op_sel_hi:[1,0]
	v_pk_mul_f32 v[4:5], v[4:5], v[186:187] op_sel_hi:[1,0]
	v_pk_mul_f32 v[2:3], v[2:3], v[186:187] op_sel_hi:[1,0]
	v_mul_f32_e32 v224, v224, v186
.Latt3_nr_5:
	v_sub_f32_e32 v82, v82, v223
	v_sub_f32_e32 v83, v83, v223
	v_sub_f32_e32 v84, v84, v223
	v_sub_f32_e32 v85, v85, v223
	v_exp_f32_e32 v82, v82
	v_exp_f32_e32 v83, v83
	v_exp_f32_e32 v84, v84
	v_exp_f32_e32 v85, v85
	v_sub_f32_e32 v86, v86, v223
	v_sub_f32_e32 v87, v87, v223
	v_sub_f32_e32 v88, v88, v223
	v_sub_f32_e32 v89, v89, v223
	v_exp_f32_e32 v86, v86
	v_exp_f32_e32 v87, v87
	v_exp_f32_e32 v88, v88
	v_exp_f32_e32 v89, v89
	v_cvt_pk_bf16_f32 v226, v82, v83
	v_cvt_pk_bf16_f32 v227, v84, v85
	v_cvt_pk_bf16_f32 v228, v86, v87
	v_cvt_pk_bf16_f32 v229, v88, v89
	s_nop 1
	v_mfma_f32_32x32x16_bf16 v[50:65], v[236:239], v[226:229], v[50:65]
	ds_read_b128 v[236:239], v205 offset:30240
	v_sub_f32_e32 v90, v90, v223
	v_sub_f32_e32 v91, v91, v223
	v_sub_f32_e32 v92, v92, v223
	v_sub_f32_e32 v93, v93, v223
	v_exp_f32_e32 v90, v90
	v_exp_f32_e32 v91, v91
	v_mfma_f32_32x32x16_bf16 v[34:49], v[240:243], v[226:229], v[34:49]
	ds_read_b128 v[240:243], v205 offset:34848
	v_exp_f32_e32 v92, v92
	v_exp_f32_e32 v93, v93
	v_sub_f32_e32 v94, v94, v223
	v_sub_f32_e32 v95, v95, v223
	v_sub_f32_e32 v96, v96, v223
	v_sub_f32_e32 v97, v97, v223
	v_mfma_f32_32x32x16_bf16 v[18:33], v[244:247], v[226:229], v[18:33]
	ds_read_b128 v[244:247], v205 offset:39456
	v_exp_f32_e32 v94, v94
	v_exp_f32_e32 v95, v95
	v_exp_f32_e32 v96, v96
	v_exp_f32_e32 v97, v97
	v_add_f32_e32 v186, 0, v82
	v_add_f32_e32 v186, v83, v186
	v_mfma_f32_32x32x16_bf16 v[2:17], v[248:251], v[226:229], v[2:17]
	ds_read_b128 v[248:251], v205 offset:25664
	v_add_f32_e32 v186, v84, v186
	v_add_f32_e32 v186, v85, v186
	v_add_f32_e32 v186, v86, v186
	v_add_f32_e32 v186, v87, v186
	v_add_f32_e32 v186, v88, v186
	v_add_f32_e32 v186, v89, v186
	v_cvt_pk_bf16_f32 v226, v90, v91
	v_cvt_pk_bf16_f32 v227, v92, v93
	v_cvt_pk_bf16_f32 v228, v94, v95
	v_cvt_pk_bf16_f32 v229, v96, v97
	s_nop 1
	v_mfma_f32_32x32x16_bf16 v[50:65], v[210:213], v[226:229], v[50:65]
	ds_read_b128 v[210:213], v205 offset:30272
	v_sub_f32_e32 v66, v66, v223
	v_sub_f32_e32 v67, v67, v223
	v_sub_f32_e32 v68, v68, v223
	v_sub_f32_e32 v69, v69, v223
	v_exp_f32_e32 v66, v66
	v_exp_f32_e32 v67, v67
	s_waitcnt lgkmcnt(4)
	v_mfma_f32_32x32x16_bf16 v[34:49], v[236:239], v[226:229], v[34:49]
	ds_read_b128 v[236:239], v205 offset:34880
	v_exp_f32_e32 v68, v68
	v_exp_f32_e32 v69, v69
	v_sub_f32_e32 v70, v70, v223
	v_sub_f32_e32 v71, v71, v223
	v_sub_f32_e32 v72, v72, v223
	v_sub_f32_e32 v73, v73, v223
	s_waitcnt lgkmcnt(4)
	v_mfma_f32_32x32x16_bf16 v[18:33], v[240:243], v[226:229], v[18:33]
	ds_read_b128 v[240:243], v205 offset:39488
	v_exp_f32_e32 v70, v70
	v_exp_f32_e32 v71, v71
	v_exp_f32_e32 v72, v72
	v_exp_f32_e32 v73, v73
	v_add_f32_e32 v186, v90, v186
	v_add_f32_e32 v186, v91, v186
	s_waitcnt lgkmcnt(4)
	v_mfma_f32_32x32x16_bf16 v[2:17], v[244:247], v[226:229], v[2:17]
	ds_read_b128 v[244:247], v205 offset:25696
	v_add_f32_e32 v186, v92, v186
	v_add_f32_e32 v186, v93, v186
	v_add_f32_e32 v186, v94, v186
	v_add_f32_e32 v186, v95, v186
	v_add_f32_e32 v186, v96, v186
	v_add_f32_e32 v186, v97, v186
	v_cvt_pk_bf16_f32 v226, v66, v67
	v_cvt_pk_bf16_f32 v227, v68, v69
	v_cvt_pk_bf16_f32 v228, v70, v71
	v_cvt_pk_bf16_f32 v229, v72, v73
	s_nop 1
	s_waitcnt lgkmcnt(4)
	v_mfma_f32_32x32x16_bf16 v[50:65], v[248:251], v[226:229], v[50:65]
	ds_read_b128 v[248:251], v205 offset:30304
	v_sub_f32_e32 v74, v74, v223
	v_sub_f32_e32 v75, v75, v223
	v_sub_f32_e32 v76, v76, v223
	v_sub_f32_e32 v77, v77, v223
	v_exp_f32_e32 v74, v74
	v_exp_f32_e32 v75, v75
	s_waitcnt lgkmcnt(4)
	v_mfma_f32_32x32x16_bf16 v[34:49], v[210:213], v[226:229], v[34:49]
	ds_read_b128 v[210:213], v205 offset:34912
	v_exp_f32_e32 v76, v76
	v_exp_f32_e32 v77, v77
	v_sub_f32_e32 v78, v78, v223
	v_sub_f32_e32 v79, v79, v223
	v_sub_f32_e32 v80, v80, v223
	v_sub_f32_e32 v81, v81, v223
	s_waitcnt lgkmcnt(4)
	v_mfma_f32_32x32x16_bf16 v[18:33], v[236:239], v[226:229], v[18:33]
	ds_read_b128 v[236:239], v205 offset:39520
	v_exp_f32_e32 v78, v78
	v_exp_f32_e32 v79, v79
	v_exp_f32_e32 v80, v80
	v_exp_f32_e32 v81, v81
	v_add_f32_e32 v186, v66, v186
	v_add_f32_e32 v186, v67, v186
	s_waitcnt lgkmcnt(4)
	v_mfma_f32_32x32x16_bf16 v[2:17], v[240:243], v[226:229], v[2:17]
	v_add_f32_e32 v186, v68, v186
	v_add_f32_e32 v186, v69, v186
	v_add_f32_e32 v186, v70, v186
	v_add_f32_e32 v186, v71, v186
	v_add_f32_e32 v186, v72, v186
	v_add_f32_e32 v186, v73, v186
	v_cvt_pk_bf16_f32 v226, v74, v75
	v_cvt_pk_bf16_f32 v227, v76, v77
	v_cvt_pk_bf16_f32 v228, v78, v79
	v_cvt_pk_bf16_f32 v229, v80, v81
	s_nop 1
	s_waitcnt lgkmcnt(3)
	v_mfma_f32_32x32x16_bf16 v[50:65], v[244:247], v[226:229], v[50:65]
	v_add_f32_e32 v186, v74, v186
	v_add_f32_e32 v186, v75, v186
	s_waitcnt lgkmcnt(2)
	v_mfma_f32_32x32x16_bf16 v[34:49], v[248:251], v[226:229], v[34:49]
	v_add_f32_e32 v186, v76, v186
	v_add_f32_e32 v186, v77, v186
	s_waitcnt lgkmcnt(1)
	v_mfma_f32_32x32x16_bf16 v[18:33], v[210:213], v[226:229], v[18:33]
	v_add_f32_e32 v186, v78, v186
	v_add_f32_e32 v186, v79, v186
	s_waitcnt lgkmcnt(0)
	s_barrier
	v_mfma_f32_32x32x16_bf16 v[2:17], v[236:239], v[226:229], v[2:17]
	v_add_f32_e32 v186, v80, v186
	v_add_f32_e32 v186, v81, v186
	v_add_f32_e32 v225, v224, v186
	s_setprio 0
	s_add_i32 s13, s11, 2
	s_cmp_ge_u32 s13, s5
	s_cbranch_scc1 .Latt3_wskip_6
	v_add_u32_e32 v206, s72, v219
	v_add_u32_e32 v208, s72, v220
	v_add_u32_e32 v186, s72, v221
	v_add_u32_e32 v187, s72, v222
	s_add_i32 s13, s11, 3
	s_cmp_ge_u32 s13, s5
	s_cbranch_scc1 .Latt3_wtail_7
	s_waitcnt vmcnt(9)
	ds_write_b128 v206, v[118:121]
	s_waitcnt vmcnt(8)
	ds_write_b128 v208, v[122:125]
	s_waitcnt vmcnt(7)
	ds_write_b128 v186, v[130:133]
	s_waitcnt vmcnt(6)
	ds_write_b128 v187, v[134:137] offset:25600
	s_waitcnt vmcnt(5)
	ds_write_b128 v187, v[138:141] offset:34816
	s_branch .Latt3_wld_8
.Latt3_wtail_7:
	s_waitcnt vmcnt(4)
	ds_write_b128 v206, v[118:121]
	s_waitcnt vmcnt(3)
	ds_write_b128 v208, v[122:125]
	s_waitcnt vmcnt(2)
	ds_write_b128 v186, v[130:133]
	s_waitcnt vmcnt(1)
	ds_write_b128 v187, v[134:137] offset:25600
	s_waitcnt vmcnt(0)
	ds_write_b128 v187, v[138:141] offset:34816
.Latt3_wld_8:
	s_add_i32 s13, s11, 4
	s_cmp_ge_u32 s13, s5
	s_cbranch_scc1 .Latt3_wdone_9
	global_load_dwordx4 v[118:121], v204, s[66:67]
	global_load_dwordx4 v[122:125], v204, s[74:75]
	global_load_dwordx4 v[130:133], v204, s[76:77]
	global_load_dwordx4 v[134:137], v207, s[68:69]
	global_load_dwordx4 v[138:141], v207, s[78:79]
	s_add_u32 s66, s66, 0x6000
	s_addc_u32 s67, s67, 0
	s_add_u32 s74, s74, 0x6000
	s_addc_u32 s75, s75, 0
	s_add_u32 s76, s76, 0x6000
	s_addc_u32 s77, s77, 0
	s_add_u32 s68, s68, 0x80
	s_addc_u32 s69, s69, 0
	s_add_u32 s78, s78, 0x80
	s_addc_u32 s79, s79, 0
.Latt3_wdone_9:
.Latt3_wskip_6:
	s_mov_b32 s13, s70
	s_mov_b32 s70, s71
	s_mov_b32 s71, s72
	s_mov_b32 s72, s13
	s_add_i32 s11, s11, 1
	v_add_u32_e32 v209, s70, v215
	v_add_u32_e32 v205, s70, v216
	ds_read_b128 v[226:229], v209
	ds_read_b128 v[236:239], v209 offset:12800
	ds_read_b128 v[240:243], v209 offset:32
	ds_read_b128 v[244:247], v209 offset:12832
	ds_read_b128 v[248:251], v209 offset:64
	ds_read_b128 v[210:213], v209 offset:12864
	s_waitcnt lgkmcnt(5)
	v_mfma_f32_32x32x16_bf16 v[82:97], v[226:229], v[126:129], 0
	ds_read_b128 v[226:229], v209 offset:96
	s_waitcnt lgkmcnt(5)
	v_mfma_f32_32x32x16_bf16 v[66:81], v[236:239], v[126:129], 0
	ds_read_b128 v[236:239], v209 offset:12896
	s_waitcnt lgkmcnt(5)
	v_mfma_f32_32x32x16_bf16 v[82:97], v[240:243], v[142:145], v[82:97]
	ds_read_b128 v[240:243], v209 offset:128
	s_waitcnt lgkmcnt(5)
	v_mfma_f32_32x32x16_bf16 v[66:81], v[244:247], v[142:145], v[66:81]
	ds_read_b128 v[244:247], v209 offset:12928
	s_waitcnt lgkmcnt(5)
	v_mfma_f32_32x32x16_bf16 v[82:97], v[248:251], v[146:149], v[82:97]
	ds_read_b128 v[248:251], v209 offset:160
	s_waitcnt lgkmcnt(5)
	v_mfma_f32_32x32x16_bf16 v[66:81], v[210:213], v[146:149], v[66:81]
	ds_read_b128 v[210:213], v209 offset:12960
	s_waitcnt lgkmcnt(5)
	v_mfma_f32_32x32x16_bf16 v[82:97], v[226:229], v[150:153], v[82:97]
	ds_read_b128 v[226:229], v209 offset:192
	s_waitcnt lgkmcnt(5)
	v_mfma_f32_32x32x16_bf16 v[66:81], v[236:239], v[150:153], v[66:81]
	ds_read_b128 v[236:239], v209 offset:12992
	s_waitcnt lgkmcnt(5)
	v_mfma_f32_32x32x16_bf16 v[82:97], v[240:243], v[154:157], v[82:97]
	ds_read_b128 v[240:243], v209 offset:224
	s_waitcnt lgkmcnt(5)
	v_mfma_f32_32x32x16_bf16 v[66:81], v[244:247], v[154:157], v[66:81]
	ds_read_b128 v[244:247], v209 offset:13024
	s_waitcnt lgkmcnt(5)
	v_mfma_f32_32x32x16_bf16 v[82:97], v[248:251], v[158:161], v[82:97]
	ds_read_b128 v[248:251], v209 offset:256
	s_waitcnt lgkmcnt(5)
	v_mfma_f32_32x32x16_bf16 v[66:81], v[210:213], v[158:161], v[66:81]
	ds_read_b128 v[210:213], v209 offset:13056
	s_waitcnt lgkmcnt(5)
	v_mfma_f32_32x32x16_bf16 v[82:97], v[226:229], v[162:165], v[82:97]
	ds_read_b128 v[226:229], v209 offset:288
	s_waitcnt lgkmcnt(5)
	v_mfma_f32_32x32x16_bf16 v[66:81], v[236:239], v[162:165], v[66:81]
	ds_read_b128 v[236:239], v209 offset:13088
	s_waitcnt lgkmcnt(5)
	v_mfma_f32_32x32x16_bf16 v[82:97], v[240:243], v[166:169], v[82:97]
	ds_read_b128 v[240:243], v209 offset:320
	s_waitcnt lgkmcnt(5)
	v_mfma_f32_32x32x16_bf16 v[66:81], v[244:247], v[166:169], v[66:81]
	ds_read_b128 v[244:247], v209 offset:13120
	s_waitcnt lgkmcnt(5)
	v_mfma_f32_32x32x16_bf16 v[82:97], v[248:251], v[170:173], v[82:97]
	ds_read_b128 v[248:251], v209 offset:352
	s_waitcnt lgkmcnt(5)
	v_mfma_f32_32x32x16_bf16 v[66:81], v[210:213], v[170:173], v[66:81]
	ds_read_b128 v[210:213], v209 offset:13152
	s_waitcnt lgkmcnt(5)
	v_mfma_f32_32x32x16_bf16 v[82:97], v[226:229], v[174:177], v[82:97]
	s_waitcnt lgkmcnt(4)
	v_mfma_f32_32x32x16_bf16 v[66:81], v[236:239], v[174:177], v[66:81]
	s_waitcnt lgkmcnt(3)
	v_mfma_f32_32x32x16_bf16 v[82:97], v[240:243], v[178:181], v[82:97]
	s_waitcnt lgkmcnt(2)
	v_mfma_f32_32x32x16_bf16 v[66:81], v[244:247], v[178:181], v[66:81]
	s_waitcnt lgkmcnt(1)
	v_mfma_f32_32x32x16_bf16 v[82:97], v[248:251], v[182:185], v[82:97]
	s_waitcnt lgkmcnt(0)
	v_mfma_f32_32x32x16_bf16 v[66:81], v[210:213], v[182:185], v[66:81]
	s_setprio 2
	ds_read_b128 v[236:239], v205 offset:25600
	ds_read_b128 v[240:243], v205 offset:30208
	ds_read_b128 v[244:247], v205 offset:34816
	ds_read_b128 v[248:251], v205 offset:39424
	ds_read_b128 v[210:213], v205 offset:25632
	s_nop 4
	v_max_f32_e32 v186, v83, v83
	v_max_f32_e32 v187, v82, v82
	v_max_f32_e32 v186, v187, v186
	v_max3_f32 v186, v186, v84, v85
	v_max3_f32 v186, v186, v86, v87
	v_max3_f32 v186, v186, v88, v89
	v_max3_f32 v186, v186, v90, v91
	v_max3_f32 v186, v186, v92, v93
	v_max3_f32 v186, v186, v94, v95
	v_max3_f32 v186, v186, v96, v97
	v_max3_f32 v186, v186, v66, v67
	v_max3_f32 v186, v186, v68, v69
	v_max3_f32 v186, v186, v70, v71
	v_max3_f32 v186, v186, v72, v73
	v_max3_f32 v186, v186, v74, v75
	v_max3_f32 v186, v186, v76, v77
	v_max3_f32 v186, v186, v78, v79
	v_max3_f32 v186, v186, v80, v81
	ds_bpermute_b32 v187, v214, v186
	s_waitcnt lgkmcnt(0)
	v_max_f32_e32 v187, v187, v187
	v_max_f32_e32 v187, v186, v187
	v_add_f32_e32 v186, 0x41380000, v223
	v_cmp_gt_f32_e32 vcc, v187, v186
	s_cbranch_vccz .Latt3_nr_10
	v_max_f32_e32 v186, v187, v187
	v_max_f32_e32 v187, v223, v223
	v_max_f32_e32 v187, v187, v186
	v_sub_f32_e32 v186, v223, v187
	v_exp_f32_e32 v186, v186
	v_mov_b32_e32 v223, v187
	v_pk_mul_f32 v[64:65], v[64:65], v[186:187] op_sel_hi:[1,0]
	v_pk_mul_f32 v[62:63], v[62:63], v[186:187] op_sel_hi:[1,0]
	v_pk_mul_f32 v[60:61], v[60:61], v[186:187] op_sel_hi:[1,0]
	v_pk_mul_f32 v[58:59], v[58:59], v[186:187] op_sel_hi:[1,0]
	v_pk_mul_f32 v[56:57], v[56:57], v[186:187] op_sel_hi:[1,0]
	v_pk_mul_f32 v[54:55], v[54:55], v[186:187] op_sel_hi:[1,0]
	v_pk_mul_f32 v[52:53], v[52:53], v[186:187] op_sel_hi:[1,0]
	v_pk_mul_f32 v[50:51], v[50:51], v[186:187] op_sel_hi:[1,0]
	v_pk_mul_f32 v[48:49], v[48:49], v[186:187] op_sel_hi:[1,0]
	v_pk_mul_f32 v[46:47], v[46:47], v[186:187] op_sel_hi:[1,0]
	v_pk_mul_f32 v[44:45], v[44:45], v[186:187] op_sel_hi:[1,0]
	v_pk_mul_f32 v[42:43], v[42:43], v[186:187] op_sel_hi:[1,0]
	v_pk_mul_f32 v[40:41], v[40:41], v[186:187] op_sel_hi:[1,0]
	v_pk_mul_f32 v[38:39], v[38:39], v[186:187] op_sel_hi:[1,0]
	v_pk_mul_f32 v[36:37], v[36:37], v[186:187] op_sel_hi:[1,0]
	v_pk_mul_f32 v[34:35], v[34:35], v[186:187] op_sel_hi:[1,0]
	v_pk_mul_f32 v[32:33], v[32:33], v[186:187] op_sel_hi:[1,0]
	v_pk_mul_f32 v[30:31], v[30:31], v[186:187] op_sel_hi:[1,0]
	v_pk_mul_f32 v[28:29], v[28:29], v[186:187] op_sel_hi:[1,0]
	v_pk_mul_f32 v[26:27], v[26:27], v[186:187] op_sel_hi:[1,0]
	v_pk_mul_f32 v[24:25], v[24:25], v[186:187] op_sel_hi:[1,0]
	v_pk_mul_f32 v[22:23], v[22:23], v[186:187] op_sel_hi:[1,0]
	v_pk_mul_f32 v[20:21], v[20:21], v[186:187] op_sel_hi:[1,0]
	v_pk_mul_f32 v[18:19], v[18:19], v[186:187] op_sel_hi:[1,0]
	v_pk_mul_f32 v[16:17], v[16:17], v[186:187] op_sel_hi:[1,0]
	v_pk_mul_f32 v[14:15], v[14:15], v[186:187] op_sel_hi:[1,0]
	v_pk_mul_f32 v[12:13], v[12:13], v[186:187] op_sel_hi:[1,0]
	v_pk_mul_f32 v[10:11], v[10:11], v[186:187] op_sel_hi:[1,0]
	v_pk_mul_f32 v[8:9], v[8:9], v[186:187] op_sel_hi:[1,0]
	v_pk_mul_f32 v[6:7], v[6:7], v[186:187] op_sel_hi:[1,0]
	v_pk_mul_f32 v[4:5], v[4:5], v[186:187] op_sel_hi:[1,0]
	v_pk_mul_f32 v[2:3], v[2:3], v[186:187] op_sel_hi:[1,0]
	v_mul_f32_e32 v225, v225, v186
.Latt3_nr_10:
	v_sub_f32_e32 v82, v82, v223
	v_sub_f32_e32 v83, v83, v223
	v_sub_f32_e32 v84, v84, v223
	v_sub_f32_e32 v85, v85, v223
	v_exp_f32_e32 v82, v82
	v_exp_f32_e32 v83, v83
	v_exp_f32_e32 v84, v84
	v_exp_f32_e32 v85, v85
	v_sub_f32_e32 v86, v86, v223
	v_sub_f32_e32 v87, v87, v223
	v_sub_f32_e32 v88, v88, v223
	v_sub_f32_e32 v89, v89, v223
	v_exp_f32_e32 v86, v86
	v_exp_f32_e32 v87, v87
	v_exp_f32_e32 v88, v88
	v_exp_f32_e32 v89, v89
	v_cvt_pk_bf16_f32 v226, v82, v83
	v_cvt_pk_bf16_f32 v227, v84, v85
	v_cvt_pk_bf16_f32 v228, v86, v87
	v_cvt_pk_bf16_f32 v229, v88, v89
	s_nop 1
	v_mfma_f32_32x32x16_bf16 v[50:65], v[236:239], v[226:229], v[50:65]
	ds_read_b128 v[236:239], v205 offset:30240
	v_sub_f32_e32 v90, v90, v223
	v_sub_f32_e32 v91, v91, v223
	v_sub_f32_e32 v92, v92, v223
	v_sub_f32_e32 v93, v93, v223
	v_exp_f32_e32 v90, v90
	v_exp_f32_e32 v91, v91
	v_mfma_f32_32x32x16_bf16 v[34:49], v[240:243], v[226:229], v[34:49]
	ds_read_b128 v[240:243], v205 offset:34848
	v_exp_f32_e32 v92, v92
	v_exp_f32_e32 v93, v93
	v_sub_f32_e32 v94, v94, v223
	v_sub_f32_e32 v95, v95, v223
	v_sub_f32_e32 v96, v96, v223
	v_sub_f32_e32 v97, v97, v223
	v_mfma_f32_32x32x16_bf16 v[18:33], v[244:247], v[226:229], v[18:33]
	ds_read_b128 v[244:247], v205 offset:39456
	v_exp_f32_e32 v94, v94
	v_exp_f32_e32 v95, v95
	v_exp_f32_e32 v96, v96
	v_exp_f32_e32 v97, v97
	v_add_f32_e32 v186, 0, v82
	v_add_f32_e32 v186, v83, v186
	v_mfma_f32_32x32x16_bf16 v[2:17], v[248:251], v[226:229], v[2:17]
	ds_read_b128 v[248:251], v205 offset:25664
	v_add_f32_e32 v186, v84, v186
	v_add_f32_e32 v186, v85, v186
	v_add_f32_e32 v186, v86, v186
	v_add_f32_e32 v186, v87, v186
	v_add_f32_e32 v186, v88, v186
	v_add_f32_e32 v186, v89, v186
	v_cvt_pk_bf16_f32 v226, v90, v91
	v_cvt_pk_bf16_f32 v227, v92, v93
	v_cvt_pk_bf16_f32 v228, v94, v95
	v_cvt_pk_bf16_f32 v229, v96, v97
	s_nop 1
	v_mfma_f32_32x32x16_bf16 v[50:65], v[210:213], v[226:229], v[50:65]
	ds_read_b128 v[210:213], v205 offset:30272
	v_sub_f32_e32 v66, v66, v223
	v_sub_f32_e32 v67, v67, v223
	v_sub_f32_e32 v68, v68, v223
	v_sub_f32_e32 v69, v69, v223
	v_exp_f32_e32 v66, v66
	v_exp_f32_e32 v67, v67
	s_waitcnt lgkmcnt(4)
	v_mfma_f32_32x32x16_bf16 v[34:49], v[236:239], v[226:229], v[34:49]
	ds_read_b128 v[236:239], v205 offset:34880
	v_exp_f32_e32 v68, v68
	v_exp_f32_e32 v69, v69
	v_sub_f32_e32 v70, v70, v223
	v_sub_f32_e32 v71, v71, v223
	v_sub_f32_e32 v72, v72, v223
	v_sub_f32_e32 v73, v73, v223
	s_waitcnt lgkmcnt(4)
	v_mfma_f32_32x32x16_bf16 v[18:33], v[240:243], v[226:229], v[18:33]
	ds_read_b128 v[240:243], v205 offset:39488
	v_exp_f32_e32 v70, v70
	v_exp_f32_e32 v71, v71
	v_exp_f32_e32 v72, v72
	v_exp_f32_e32 v73, v73
	v_add_f32_e32 v186, v90, v186
	v_add_f32_e32 v186, v91, v186
	s_waitcnt lgkmcnt(4)
	v_mfma_f32_32x32x16_bf16 v[2:17], v[244:247], v[226:229], v[2:17]
	ds_read_b128 v[244:247], v205 offset:25696
	v_add_f32_e32 v186, v92, v186
	v_add_f32_e32 v186, v93, v186
	v_add_f32_e32 v186, v94, v186
	v_add_f32_e32 v186, v95, v186
	v_add_f32_e32 v186, v96, v186
	v_add_f32_e32 v186, v97, v186
	v_cvt_pk_bf16_f32 v226, v66, v67
	v_cvt_pk_bf16_f32 v227, v68, v69
	v_cvt_pk_bf16_f32 v228, v70, v71
	v_cvt_pk_bf16_f32 v229, v72, v73
	s_nop 1
	s_waitcnt lgkmcnt(4)
	v_mfma_f32_32x32x16_bf16 v[50:65], v[248:251], v[226:229], v[50:65]
	ds_read_b128 v[248:251], v205 offset:30304
	v_sub_f32_e32 v74, v74, v223
	v_sub_f32_e32 v75, v75, v223
	v_sub_f32_e32 v76, v76, v223
	v_sub_f32_e32 v77, v77, v223
	v_exp_f32_e32 v74, v74
	v_exp_f32_e32 v75, v75
	s_waitcnt lgkmcnt(4)
	v_mfma_f32_32x32x16_bf16 v[34:49], v[210:213], v[226:229], v[34:49]
	ds_read_b128 v[210:213], v205 offset:34912
	v_exp_f32_e32 v76, v76
	v_exp_f32_e32 v77, v77
	v_sub_f32_e32 v78, v78, v223
	v_sub_f32_e32 v79, v79, v223
	v_sub_f32_e32 v80, v80, v223
	v_sub_f32_e32 v81, v81, v223
	s_waitcnt lgkmcnt(4)
	v_mfma_f32_32x32x16_bf16 v[18:33], v[236:239], v[226:229], v[18:33]
	ds_read_b128 v[236:239], v205 offset:39520
	v_exp_f32_e32 v78, v78
	v_exp_f32_e32 v79, v79
	v_exp_f32_e32 v80, v80
	v_exp_f32_e32 v81, v81
	v_add_f32_e32 v186, v66, v186
	v_add_f32_e32 v186, v67, v186
	s_waitcnt lgkmcnt(4)
	v_mfma_f32_32x32x16_bf16 v[2:17], v[240:243], v[226:229], v[2:17]
	v_add_f32_e32 v186, v68, v186
	v_add_f32_e32 v186, v69, v186
	v_add_f32_e32 v186, v70, v186
	v_add_f32_e32 v186, v71, v186
	v_add_f32_e32 v186, v72, v186
	v_add_f32_e32 v186, v73, v186
	v_cvt_pk_bf16_f32 v226, v74, v75
	v_cvt_pk_bf16_f32 v227, v76, v77
	v_cvt_pk_bf16_f32 v228, v78, v79
	v_cvt_pk_bf16_f32 v229, v80, v81
	s_nop 1
	s_waitcnt lgkmcnt(3)
	v_mfma_f32_32x32x16_bf16 v[50:65], v[244:247], v[226:229], v[50:65]
	v_add_f32_e32 v186, v74, v186
	v_add_f32_e32 v186, v75, v186
	s_waitcnt lgkmcnt(2)
	v_mfma_f32_32x32x16_bf16 v[34:49], v[248:251], v[226:229], v[34:49]
	v_add_f32_e32 v186, v76, v186
	v_add_f32_e32 v186, v77, v186
	s_waitcnt lgkmcnt(1)
	v_mfma_f32_32x32x16_bf16 v[18:33], v[210:213], v[226:229], v[18:33]
	v_add_f32_e32 v186, v78, v186
	v_add_f32_e32 v186, v79, v186
	s_waitcnt lgkmcnt(0)
	s_barrier
	v_mfma_f32_32x32x16_bf16 v[2:17], v[236:239], v[226:229], v[2:17]
	v_add_f32_e32 v186, v80, v186
	v_add_f32_e32 v186, v81, v186
	v_add_f32_e32 v224, v225, v186
	s_setprio 0
	s_add_i32 s13, s11, 2
	s_cmp_ge_u32 s13, s5
	s_cbranch_scc1 .Latt3_wskip_11
	v_add_u32_e32 v206, s72, v219
	v_add_u32_e32 v208, s72, v220
	v_add_u32_e32 v186, s72, v221
	v_add_u32_e32 v187, s72, v222
	s_add_i32 s13, s11, 3
	s_cmp_ge_u32 s13, s5
	s_cbranch_scc1 .Latt3_wtail_12
	s_waitcnt vmcnt(9)
	ds_write_b128 v206, v[102:105]
	s_waitcnt vmcnt(8)
	ds_write_b128 v208, v[106:109]
	s_waitcnt vmcnt(7)
	ds_write_b128 v186, v[114:117]
	s_waitcnt vmcnt(6)
	ds_write_b128 v187, v[98:101] offset:25600
	s_waitcnt vmcnt(5)
	ds_write_b128 v187, v[110:113] offset:34816
	s_branch .Latt3_wld_13

.Latt3_wdone_14:
.Latt3_wskip_11:
	s_mov_b32 s13, s70
	s_mov_b32 s70, s71
	s_mov_b32 s71, s72
	s_mov_b32 s72, s13
	s_add_i32 s11, s11, 1
	s_cmp_ge_u32 s11, s5
	s_cbranch_scc0 .Latt3_A_loop
	s_branch .Latt3_exit
.Latt3_B_loop:
	v_add_u32_e32 v209, s70, v215
	v_add_u32_e32 v205, s70, v216
	ds_read_b128 v[226:229], v209
	ds_read_b128 v[236:239], v209 offset:12800
	ds_read_b128 v[240:243], v209 offset:32
	ds_read_b128 v[244:247], v209 offset:12832
	ds_read_b128 v[248:251], v209 offset:64
	ds_read_b128 v[210:213], v209 offset:12864
	s_waitcnt lgkmcnt(5)
	v_mfma_f32_32x32x16_bf16 v[82:97], v[226:229], v[126:129], 0
	ds_read_b128 v[226:229], v209 offset:96
	s_waitcnt lgkmcnt(5)
	v_mfma_f32_32x32x16_bf16 v[66:81], v[236:239], v[126:129], 0
	ds_read_b128 v[236:239], v209 offset:12896
	s_waitcnt lgkmcnt(5)
	v_mfma_f32_32x32x16_bf16 v[82:97], v[240:243], v[142:145], v[82:97]
	ds_read_b128 v[240:243], v209 offset:128
	s_waitcnt lgkmcnt(5)
	v_mfma_f32_32x32x16_bf16 v[66:81], v[244:247], v[142:145], v[66:81]
	ds_read_b128 v[244:247], v209 offset:12928
	s_waitcnt lgkmcnt(5)
	v_mfma_f32_32x32x16_bf16 v[82:97], v[248:251], v[146:149], v[82:97]
	ds_read_b128 v[248:251], v209 offset:160
	s_waitcnt lgkmcnt(5)
	v_mfma_f32_32x32x16_bf16 v[66:81], v[210:213], v[146:149], v[66:81]
	ds_read_b128 v[210:213], v209 offset:12960
	s_waitcnt lgkmcnt(5)
	v_mfma_f32_32x32x16_bf16 v[82:97], v[226:229], v[150:153], v[82:97]
	ds_read_b128 v[226:229], v209 offset:192
	s_waitcnt lgkmcnt(5)
	v_mfma_f32_32x32x16_bf16 v[66:81], v[236:239], v[150:153], v[66:81]
	ds_read_b128 v[236:239], v209 offset:12992
	s_waitcnt lgkmcnt(5)
	v_mfma_f32_32x32x16_bf16 v[82:97], v[240:243], v[154:157], v[82:97]
	ds_read_b128 v[240:243], v209 offset:224
	s_waitcnt lgkmcnt(5)
	v_mfma_f32_32x32x16_bf16 v[66:81], v[244:247], v[154:157], v[66:81]
	ds_read_b128 v[244:247], v209 offset:13024
	s_waitcnt lgkmcnt(5)
	v_mfma_f32_32x32x16_bf16 v[82:97], v[248:251], v[158:161], v[82:97]
	ds_read_b128 v[248:251], v209 offset:256
	s_waitcnt lgkmcnt(5)
	v_mfma_f32_32x32x16_bf16 v[66:81], v[210:213], v[158:161], v[66:81]
	ds_read_b128 v[210:213], v209 offset:13056
	s_waitcnt lgkmcnt(5)
	v_mfma_f32_32x32x16_bf16 v[82:97], v[226:229], v[162:165], v[82:97]
	ds_read_b128 v[226:229], v209 offset:288
	s_waitcnt lgkmcnt(5)
	v_mfma_f32_32x32x16_bf16 v[66:81], v[236:239], v[162:165], v[66:81]
	ds_read_b128 v[236:239], v209 offset:13088
	s_waitcnt lgkmcnt(5)
	v_mfma_f32_32x32x16_bf16 v[82:97], v[240:243], v[166:169], v[82:97]
	ds_read_b128 v[240:243], v209 offset:320
	s_waitcnt lgkmcnt(5)
	v_mfma_f32_32x32x16_bf16 v[66:81], v[244:247], v[166:169], v[66:81]
	ds_read_b128 v[244:247], v209 offset:13120
	s_waitcnt lgkmcnt(5)
	v_mfma_f32_32x32x16_bf16 v[82:97], v[248:251], v[170:173], v[82:97]
	ds_read_b128 v[248:251], v209 offset:352
	s_waitcnt lgkmcnt(5)
	v_mfma_f32_32x32x16_bf16 v[66:81], v[210:213], v[170:173], v[66:81]
	ds_read_b128 v[210:213], v209 offset:13152
	s_waitcnt lgkmcnt(5)
	v_mfma_f32_32x32x16_bf16 v[82:97], v[226:229], v[174:177], v[82:97]
	s_waitcnt lgkmcnt(4)
	v_mfma_f32_32x32x16_bf16 v[66:81], v[236:239], v[174:177], v[66:81]
	s_waitcnt lgkmcnt(3)
	v_mfma_f32_32x32x16_bf16 v[82:97], v[240:243], v[178:181], v[82:97]
	s_waitcnt lgkmcnt(2)
	v_mfma_f32_32x32x16_bf16 v[66:81], v[244:247], v[178:181], v[66:81]
	s_waitcnt lgkmcnt(1)
	v_mfma_f32_32x32x16_bf16 v[82:97], v[248:251], v[182:185], v[82:97]
	s_waitcnt lgkmcnt(0)
	s_barrier
	v_mfma_f32_32x32x16_bf16 v[66:81], v[210:213], v[182:185], v[66:81]
	s_setprio 2
	ds_read_b128 v[236:239], v205 offset:25600
	ds_read_b128 v[240:243], v205 offset:30208
	ds_read_b128 v[244:247], v205 offset:34816
	ds_read_b128 v[248:251], v205 offset:39424
	ds_read_b128 v[210:213], v205 offset:25632
	s_nop 4
	v_max_f32_e32 v186, v83, v83
	v_max_f32_e32 v187, v82, v82
	v_max_f32_e32 v186, v187, v186
	v_max3_f32 v186, v186, v84, v85
	v_max3_f32 v186, v186, v86, v87
	v_max3_f32 v186, v186, v88, v89
	v_max3_f32 v186, v186, v90, v91
	v_max3_f32 v186, v186, v92, v93
	v_max3_f32 v186, v186, v94, v95
	v_max3_f32 v186, v186, v96, v97
	v_max3_f32 v186, v186, v66, v67
	v_max3_f32 v186, v186, v68, v69
	v_max3_f32 v186, v186, v70, v71
	v_max3_f32 v186, v186, v72, v73
	v_max3_f32 v186, v186, v74, v75
	v_max3_f32 v186, v186, v76, v77
	v_max3_f32 v186, v186, v78, v79
	v_max3_f32 v186, v186, v80, v81
	ds_bpermute_b32 v187, v214, v186
	s_waitcnt lgkmcnt(0)
	v_max_f32_e32 v187, v187, v187
	v_max_f32_e32 v187, v186, v187
	v_add_f32_e32 v186, 0x41380000, v223
	v_cmp_gt_f32_e32 vcc, v187, v186
	s_cbranch_vccz .Latt3_nr_15
	v_max_f32_e32 v186, v187, v187
	v_max_f32_e32 v187, v223, v223
	v_max_f32_e32 v187, v187, v186
	v_sub_f32_e32 v186, v223, v187
	v_exp_f32_e32 v186, v186
	v_mov_b32_e32 v223, v187
	v_pk_mul_f32 v[64:65], v[64:65], v[186:187] op_sel_hi:[1,0]
	v_pk_mul_f32 v[62:63], v[62:63], v[186:187] op_sel_hi:[1,0]
	v_pk_mul_f32 v[60:61], v[60:61], v[186:187] op_sel_hi:[1,0]
	v_pk_mul_f32 v[58:59], v[58:59], v[186:187] op_sel_hi:[1,0]
	v_pk_mul_f32 v[56:57], v[56:57], v[186:187] op_sel_hi:[1,0]
	v_pk_mul_f32 v[54:55], v[54:55], v[186:187] op_sel_hi:[1,0]
	v_pk_mul_f32 v[52:53], v[52:53], v[186:187] op_sel_hi:[1,0]
	v_pk_mul_f32 v[50:51], v[50:51], v[186:187] op_sel_hi:[1,0]
	v_pk_mul_f32 v[48:49], v[48:49], v[186:187] op_sel_hi:[1,0]
	v_pk_mul_f32 v[46:47], v[46:47], v[186:187] op_sel_hi:[1,0]
	v_pk_mul_f32 v[44:45], v[44:45], v[186:187] op_sel_hi:[1,0]
	v_pk_mul_f32 v[42:43], v[42:43], v[186:187] op_sel_hi:[1,0]
	v_pk_mul_f32 v[40:41], v[40:41], v[186:187] op_sel_hi:[1,0]
	v_pk_mul_f32 v[38:39], v[38:39], v[186:187] op_sel_hi:[1,0]
	v_pk_mul_f32 v[36:37], v[36:37], v[186:187] op_sel_hi:[1,0]
	v_pk_mul_f32 v[34:35], v[34:35], v[186:187] op_sel_hi:[1,0]
	v_pk_mul_f32 v[32:33], v[32:33], v[186:187] op_sel_hi:[1,0]
	v_pk_mul_f32 v[30:31], v[30:31], v[186:187] op_sel_hi:[1,0]
	v_pk_mul_f32 v[28:29], v[28:29], v[186:187] op_sel_hi:[1,0]
	v_pk_mul_f32 v[26:27], v[26:27], v[186:187] op_sel_hi:[1,0]
	v_pk_mul_f32 v[24:25], v[24:25], v[186:187] op_sel_hi:[1,0]
	v_pk_mul_f32 v[22:23], v[22:23], v[186:187] op_sel_hi:[1,0]
	v_pk_mul_f32 v[20:21], v[20:21], v[186:187] op_sel_hi:[1,0]
	v_pk_mul_f32 v[18:19], v[18:19], v[186:187] op_sel_hi:[1,0]
	v_pk_mul_f32 v[16:17], v[16:17], v[186:187] op_sel_hi:[1,0]
	v_pk_mul_f32 v[14:15], v[14:15], v[186:187] op_sel_hi:[1,0]
	v_pk_mul_f32 v[12:13], v[12:13], v[186:187] op_sel_hi:[1,0]
	v_pk_mul_f32 v[10:11], v[10:11], v[186:187] op_sel_hi:[1,0]
	v_pk_mul_f32 v[8:9], v[8:9], v[186:187] op_sel_hi:[1,0]
	v_pk_mul_f32 v[6:7], v[6:7], v[186:187] op_sel_hi:[1,0]
	v_pk_mul_f32 v[4:5], v[4:5], v[186:187] op_sel_hi:[1,0]
	v_pk_mul_f32 v[2:3], v[2:3], v[186:187] op_sel_hi:[1,0]
	v_mul_f32_e32 v224, v224, v186
.Latt3_nr_15:
	v_sub_f32_e32 v82, v82, v223
	v_sub_f32_e32 v83, v83, v223
	v_sub_f32_e32 v84, v84, v223
	v_sub_f32_e32 v85, v85, v223
	v_exp_f32_e32 v82, v82
	v_exp_f32_e32 v83, v83
	v_exp_f32_e32 v84, v84
	v_exp_f32_e32 v85, v85
	v_sub_f32_e32 v86, v86, v223
	v_sub_f32_e32 v87, v87, v223
	v_sub_f32_e32 v88, v88, v223
	v_sub_f32_e32 v89, v89, v223
	v_exp_f32_e32 v86, v86
	v_exp_f32_e32 v87, v87
	v_exp_f32_e32 v88, v88
	v_exp_f32_e32 v89, v89
	v_cvt_pk_bf16_f32 v226, v82, v83
	v_cvt_pk_bf16_f32 v227, v84, v85
	v_cvt_pk_bf16_f32 v228, v86, v87
	v_cvt_pk_bf16_f32 v229, v88, v89
	s_nop 1
	v_mfma_f32_32x32x16_bf16 v[50:65], v[236:239], v[226:229], v[50:65]
	ds_read_b128 v[236:239], v205 offset:30240
	v_sub_f32_e32 v90, v90, v223
	v_sub_f32_e32 v91, v91, v223
	v_sub_f32_e32 v92, v92, v223
	v_sub_f32_e32 v93, v93, v223
	v_exp_f32_e32 v90, v90
	v_exp_f32_e32 v91, v91
	v_mfma_f32_32x32x16_bf16 v[34:49], v[240:243], v[226:229], v[34:49]
	ds_read_b128 v[240:243], v205 offset:34848
	v_exp_f32_e32 v92, v92
	v_exp_f32_e32 v93, v93
	v_sub_f32_e32 v94, v94, v223
	v_sub_f32_e32 v95, v95, v223
	v_sub_f32_e32 v96, v96, v223
	v_sub_f32_e32 v97, v97, v223
	v_mfma_f32_32x32x16_bf16 v[18:33], v[244:247], v[226:229], v[18:33]
	ds_read_b128 v[244:247], v205 offset:39456
	v_exp_f32_e32 v94, v94
	v_exp_f32_e32 v95, v95
	v_exp_f32_e32 v96, v96
	v_exp_f32_e32 v97, v97
	v_add_f32_e32 v186, 0, v82
	v_add_f32_e32 v186, v83, v186
	v_mfma_f32_32x32x16_bf16 v[2:17], v[248:251], v[226:229], v[2:17]
	ds_read_b128 v[248:251], v205 offset:25664
	v_add_f32_e32 v186, v84, v186
	v_add_f32_e32 v186, v85, v186
	v_add_f32_e32 v186, v86, v186
	v_add_f32_e32 v186, v87, v186
	v_add_f32_e32 v186, v88, v186
	v_add_f32_e32 v186, v89, v186
	v_cvt_pk_bf16_f32 v226, v90, v91
	v_cvt_pk_bf16_f32 v227, v92, v93
	v_cvt_pk_bf16_f32 v228, v94, v95
	v_cvt_pk_bf16_f32 v229, v96, v97
	s_nop 1
	v_mfma_f32_32x32x16_bf16 v[50:65], v[210:213], v[226:229], v[50:65]
	ds_read_b128 v[210:213], v205 offset:30272
	v_sub_f32_e32 v66, v66, v223
	v_sub_f32_e32 v67, v67, v223
	v_sub_f32_e32 v68, v68, v223
	v_sub_f32_e32 v69, v69, v223
	v_exp_f32_e32 v66, v66
	v_exp_f32_e32 v67, v67
	s_waitcnt lgkmcnt(4)
	v_mfma_f32_32x32x16_bf16 v[34:49], v[236:239], v[226:229], v[34:49]
	ds_read_b128 v[236:239], v205 offset:34880
	v_exp_f32_e32 v68, v68
	v_exp_f32_e32 v69, v69
	v_sub_f32_e32 v70, v70, v223
	v_sub_f32_e32 v71, v71, v223
	v_sub_f32_e32 v72, v72, v223
	v_sub_f32_e32 v73, v73, v223
	s_waitcnt lgkmcnt(4)
	v_mfma_f32_32x32x16_bf16 v[18:33], v[240:243], v[226:229], v[18:33]
	ds_read_b128 v[240:243], v205 offset:39488
	v_exp_f32_e32 v70, v70
	v_exp_f32_e32 v71, v71
	v_exp_f32_e32 v72, v72
	v_exp_f32_e32 v73, v73
	v_add_f32_e32 v186, v90, v186
	v_add_f32_e32 v186, v91, v186
	s_waitcnt lgkmcnt(4)
	v_mfma_f32_32x32x16_bf16 v[2:17], v[244:247], v[226:229], v[2:17]
	ds_read_b128 v[244:247], v205 offset:25696
	v_add_f32_e32 v186, v92, v186
	v_add_f32_e32 v186, v93, v186
	v_add_f32_e32 v186, v94, v186
	v_add_f32_e32 v186, v95, v186
	v_add_f32_e32 v186, v96, v186
	v_add_f32_e32 v186, v97, v186
	v_cvt_pk_bf16_f32 v226, v66, v67
	v_cvt_pk_bf16_f32 v227, v68, v69
	v_cvt_pk_bf16_f32 v228, v70, v71
	v_cvt_pk_bf16_f32 v229, v72, v73
	s_nop 1
	s_waitcnt lgkmcnt(4)
	v_mfma_f32_32x32x16_bf16 v[50:65], v[248:251], v[226:229], v[50:65]
	ds_read_b128 v[248:251], v205 offset:30304
	v_sub_f32_e32 v74, v74, v223
	v_sub_f32_e32 v75, v75, v223
	v_sub_f32_e32 v76, v76, v223
	v_sub_f32_e32 v77, v77, v223
	v_exp_f32_e32 v74, v74
	v_exp_f32_e32 v75, v75
	s_waitcnt lgkmcnt(4)
	v_mfma_f32_32x32x16_bf16 v[34:49], v[210:213], v[226:229], v[34:49]
	ds_read_b128 v[210:213], v205 offset:34912
	v_exp_f32_e32 v76, v76
	v_exp_f32_e32 v77, v77
	v_sub_f32_e32 v78, v78, v223
	v_sub_f32_e32 v79, v79, v223
	v_sub_f32_e32 v80, v80, v223
	v_sub_f32_e32 v81, v81, v223
	s_waitcnt lgkmcnt(4)
	v_mfma_f32_32x32x16_bf16 v[18:33], v[236:239], v[226:229], v[18:33]
	ds_read_b128 v[236:239], v205 offset:39520
	v_exp_f32_e32 v78, v78
	v_exp_f32_e32 v79, v79
	v_exp_f32_e32 v80, v80
	v_exp_f32_e32 v81, v81
	v_add_f32_e32 v186, v66, v186
	v_add_f32_e32 v186, v67, v186
	s_waitcnt lgkmcnt(4)
	v_mfma_f32_32x32x16_bf16 v[2:17], v[240:243], v[226:229], v[2:17]
	v_add_f32_e32 v186, v68, v186
	v_add_f32_e32 v186, v69, v186
	v_add_f32_e32 v186, v70, v186
	v_add_f32_e32 v186, v71, v186
	v_add_f32_e32 v186, v72, v186
	v_add_f32_e32 v186, v73, v186
	v_cvt_pk_bf16_f32 v226, v74, v75
	v_cvt_pk_bf16_f32 v227, v76, v77
	v_cvt_pk_bf16_f32 v228, v78, v79
	v_cvt_pk_bf16_f32 v229, v80, v81
	s_nop 1
	s_waitcnt lgkmcnt(3)
	v_mfma_f32_32x32x16_bf16 v[50:65], v[244:247], v[226:229], v[50:65]
	v_add_f32_e32 v186, v74, v186
	v_add_f32_e32 v186, v75, v186
	s_waitcnt lgkmcnt(2)
	v_mfma_f32_32x32x16_bf16 v[34:49], v[248:251], v[226:229], v[34:49]
	v_add_f32_e32 v186, v76, v186
	v_add_f32_e32 v186, v77, v186
	s_waitcnt lgkmcnt(1)
	v_mfma_f32_32x32x16_bf16 v[18:33], v[210:213], v[226:229], v[18:33]
	v_add_f32_e32 v186, v78, v186
	v_add_f32_e32 v186, v79, v186
	s_waitcnt lgkmcnt(0)
	v_mfma_f32_32x32x16_bf16 v[2:17], v[236:239], v[226:229], v[2:17]
	v_add_f32_e32 v186, v80, v186
	v_add_f32_e32 v186, v81, v186
	v_add_f32_e32 v225, v224, v186
	s_setprio 0
	s_add_i32 s13, s11, 2
	s_cmp_ge_u32 s13, s5
	s_cbranch_scc1 .Latt3_wskip_16
	v_add_u32_e32 v206, s72, v219
	v_add_u32_e32 v208, s72, v220
	v_add_u32_e32 v186, s72, v221
	v_add_u32_e32 v187, s72, v222
	s_add_i32 s13, s11, 3
	s_cmp_ge_u32 s13, s5
	s_cbranch_scc1 .Latt3_wtail_17
	s_waitcnt vmcnt(9)
	ds_write_b128 v206, v[118:121]
	s_waitcnt vmcnt(8)
	ds_write_b128 v208, v[122:125]
	s_waitcnt vmcnt(7)
	ds_write_b128 v186, v[130:133]
	s_waitcnt vmcnt(6)
	ds_write_b128 v187, v[134:137] offset:25600
	s_waitcnt vmcnt(5)
	ds_write_b128 v187, v[138:141] offset:34816
	s_branch .Latt3_wld_18

.Latt3_wdone_19:
.Latt3_wskip_16:
	s_mov_b32 s13, s70
	s_mov_b32 s70, s71
	s_mov_b32 s71, s72
	s_mov_b32 s72, s13
	s_add_i32 s11, s11, 1
	v_add_u32_e32 v209, s70, v215
	v_add_u32_e32 v205, s70, v216
	ds_read_b128 v[226:229], v209
	ds_read_b128 v[236:239], v209 offset:12800
	ds_read_b128 v[240:243], v209 offset:32
	ds_read_b128 v[244:247], v209 offset:12832
	ds_read_b128 v[248:251], v209 offset:64
	ds_read_b128 v[210:213], v209 offset:12864
	s_waitcnt lgkmcnt(5)
	v_mfma_f32_32x32x16_bf16 v[82:97], v[226:229], v[126:129], 0
	ds_read_b128 v[226:229], v209 offset:96
	s_waitcnt lgkmcnt(5)
	v_mfma_f32_32x32x16_bf16 v[66:81], v[236:239], v[126:129], 0
	ds_read_b128 v[236:239], v209 offset:12896
	s_waitcnt lgkmcnt(5)
	v_mfma_f32_32x32x16_bf16 v[82:97], v[240:243], v[142:145], v[82:97]
	ds_read_b128 v[240:243], v209 offset:128
	s_waitcnt lgkmcnt(5)
	v_mfma_f32_32x32x16_bf16 v[66:81], v[244:247], v[142:145], v[66:81]
	ds_read_b128 v[244:247], v209 offset:12928
	s_waitcnt lgkmcnt(5)
	v_mfma_f32_32x32x16_bf16 v[82:97], v[248:251], v[146:149], v[82:97]
	ds_read_b128 v[248:251], v209 offset:160
	s_waitcnt lgkmcnt(5)
	v_mfma_f32_32x32x16_bf16 v[66:81], v[210:213], v[146:149], v[66:81]
	ds_read_b128 v[210:213], v209 offset:12960
	s_waitcnt lgkmcnt(5)
	v_mfma_f32_32x32x16_bf16 v[82:97], v[226:229], v[150:153], v[82:97]
	ds_read_b128 v[226:229], v209 offset:192
	s_waitcnt lgkmcnt(5)
	v_mfma_f32_32x32x16_bf16 v[66:81], v[236:239], v[150:153], v[66:81]
	ds_read_b128 v[236:239], v209 offset:12992
	s_waitcnt lgkmcnt(5)
	v_mfma_f32_32x32x16_bf16 v[82:97], v[240:243], v[154:157], v[82:97]
	ds_read_b128 v[240:243], v209 offset:224
	s_waitcnt lgkmcnt(5)
	v_mfma_f32_32x32x16_bf16 v[66:81], v[244:247], v[154:157], v[66:81]
	ds_read_b128 v[244:247], v209 offset:13024
	s_waitcnt lgkmcnt(5)
	v_mfma_f32_32x32x16_bf16 v[82:97], v[248:251], v[158:161], v[82:97]
	ds_read_b128 v[248:251], v209 offset:256
	s_waitcnt lgkmcnt(5)
	v_mfma_f32_32x32x16_bf16 v[66:81], v[210:213], v[158:161], v[66:81]
	ds_read_b128 v[210:213], v209 offset:13056
	s_waitcnt lgkmcnt(5)
	v_mfma_f32_32x32x16_bf16 v[82:97], v[226:229], v[162:165], v[82:97]
	ds_read_b128 v[226:229], v209 offset:288
	s_waitcnt lgkmcnt(5)
	v_mfma_f32_32x32x16_bf16 v[66:81], v[236:239], v[162:165], v[66:81]
	ds_read_b128 v[236:239], v209 offset:13088
	s_waitcnt lgkmcnt(5)
	v_mfma_f32_32x32x16_bf16 v[82:97], v[240:243], v[166:169], v[82:97]
	ds_read_b128 v[240:243], v209 offset:320
	s_waitcnt lgkmcnt(5)
	v_mfma_f32_32x32x16_bf16 v[66:81], v[244:247], v[166:169], v[66:81]
	ds_read_b128 v[244:247], v209 offset:13120
	s_waitcnt lgkmcnt(5)
	v_mfma_f32_32x32x16_bf16 v[82:97], v[248:251], v[170:173], v[82:97]
	ds_read_b128 v[248:251], v209 offset:352
	s_waitcnt lgkmcnt(5)
	v_mfma_f32_32x32x16_bf16 v[66:81], v[210:213], v[170:173], v[66:81]
	ds_read_b128 v[210:213], v209 offset:13152
	s_waitcnt lgkmcnt(5)
	v_mfma_f32_32x32x16_bf16 v[82:97], v[226:229], v[174:177], v[82:97]
	s_waitcnt lgkmcnt(4)
	v_mfma_f32_32x32x16_bf16 v[66:81], v[236:239], v[174:177], v[66:81]
	s_waitcnt lgkmcnt(3)
	v_mfma_f32_32x32x16_bf16 v[82:97], v[240:243], v[178:181], v[82:97]
	s_waitcnt lgkmcnt(2)
	v_mfma_f32_32x32x16_bf16 v[66:81], v[244:247], v[178:181], v[66:81]
	s_waitcnt lgkmcnt(1)
	v_mfma_f32_32x32x16_bf16 v[82:97], v[248:251], v[182:185], v[82:97]
	s_waitcnt lgkmcnt(0)
	s_barrier
	v_mfma_f32_32x32x16_bf16 v[66:81], v[210:213], v[182:185], v[66:81]
	s_setprio 2
	ds_read_b128 v[236:239], v205 offset:25600
	ds_read_b128 v[240:243], v205 offset:30208
	ds_read_b128 v[244:247], v205 offset:34816
	ds_read_b128 v[248:251], v205 offset:39424
	ds_read_b128 v[210:213], v205 offset:25632
	s_nop 4
	v_max_f32_e32 v186, v83, v83
	v_max_f32_e32 v187, v82, v82
	v_max_f32_e32 v186, v187, v186
	v_max3_f32 v186, v186, v84, v85
	v_max3_f32 v186, v186, v86, v87
	v_max3_f32 v186, v186, v88, v89
	v_max3_f32 v186, v186, v90, v91
	v_max3_f32 v186, v186, v92, v93
	v_max3_f32 v186, v186, v94, v95
	v_max3_f32 v186, v186, v96, v97
	v_max3_f32 v186, v186, v66, v67
	v_max3_f32 v186, v186, v68, v69
	v_max3_f32 v186, v186, v70, v71
	v_max3_f32 v186, v186, v72, v73
	v_max3_f32 v186, v186, v74, v75
	v_max3_f32 v186, v186, v76, v77
	v_max3_f32 v186, v186, v78, v79
	v_max3_f32 v186, v186, v80, v81
	ds_bpermute_b32 v187, v214, v186
	s_waitcnt lgkmcnt(0)
	v_max_f32_e32 v187, v187, v187
	v_max_f32_e32 v187, v186, v187
	v_add_f32_e32 v186, 0x41380000, v223
	v_cmp_gt_f32_e32 vcc, v187, v186
	s_cbranch_vccz .Latt3_nr_20
	v_max_f32_e32 v186, v187, v187
	v_max_f32_e32 v187, v223, v223
	v_max_f32_e32 v187, v187, v186
	v_sub_f32_e32 v186, v223, v187
	v_exp_f32_e32 v186, v186
	v_mov_b32_e32 v223, v187
	v_pk_mul_f32 v[64:65], v[64:65], v[186:187] op_sel_hi:[1,0]
	v_pk_mul_f32 v[62:63], v[62:63], v[186:187] op_sel_hi:[1,0]
	v_pk_mul_f32 v[60:61], v[60:61], v[186:187] op_sel_hi:[1,0]
	v_pk_mul_f32 v[58:59], v[58:59], v[186:187] op_sel_hi:[1,0]
	v_pk_mul_f32 v[56:57], v[56:57], v[186:187] op_sel_hi:[1,0]
	v_pk_mul_f32 v[54:55], v[54:55], v[186:187] op_sel_hi:[1,0]
	v_pk_mul_f32 v[52:53], v[52:53], v[186:187] op_sel_hi:[1,0]
	v_pk_mul_f32 v[50:51], v[50:51], v[186:187] op_sel_hi:[1,0]
	v_pk_mul_f32 v[48:49], v[48:49], v[186:187] op_sel_hi:[1,0]
	v_pk_mul_f32 v[46:47], v[46:47], v[186:187] op_sel_hi:[1,0]
	v_pk_mul_f32 v[44:45], v[44:45], v[186:187] op_sel_hi:[1,0]
	v_pk_mul_f32 v[42:43], v[42:43], v[186:187] op_sel_hi:[1,0]
	v_pk_mul_f32 v[40:41], v[40:41], v[186:187] op_sel_hi:[1,0]
	v_pk_mul_f32 v[38:39], v[38:39], v[186:187] op_sel_hi:[1,0]
	v_pk_mul_f32 v[36:37], v[36:37], v[186:187] op_sel_hi:[1,0]
	v_pk_mul_f32 v[34:35], v[34:35], v[186:187] op_sel_hi:[1,0]
	v_pk_mul_f32 v[32:33], v[32:33], v[186:187] op_sel_hi:[1,0]
	v_pk_mul_f32 v[30:31], v[30:31], v[186:187] op_sel_hi:[1,0]
	v_pk_mul_f32 v[28:29], v[28:29], v[186:187] op_sel_hi:[1,0]
	v_pk_mul_f32 v[26:27], v[26:27], v[186:187] op_sel_hi:[1,0]
	v_pk_mul_f32 v[24:25], v[24:25], v[186:187] op_sel_hi:[1,0]
	v_pk_mul_f32 v[22:23], v[22:23], v[186:187] op_sel_hi:[1,0]
	v_pk_mul_f32 v[20:21], v[20:21], v[186:187] op_sel_hi:[1,0]
	v_pk_mul_f32 v[18:19], v[18:19], v[186:187] op_sel_hi:[1,0]
	v_pk_mul_f32 v[16:17], v[16:17], v[186:187] op_sel_hi:[1,0]
	v_pk_mul_f32 v[14:15], v[14:15], v[186:187] op_sel_hi:[1,0]
	v_pk_mul_f32 v[12:13], v[12:13], v[186:187] op_sel_hi:[1,0]
	v_pk_mul_f32 v[10:11], v[10:11], v[186:187] op_sel_hi:[1,0]
	v_pk_mul_f32 v[8:9], v[8:9], v[186:187] op_sel_hi:[1,0]
	v_pk_mul_f32 v[6:7], v[6:7], v[186:187] op_sel_hi:[1,0]
	v_pk_mul_f32 v[4:5], v[4:5], v[186:187] op_sel_hi:[1,0]
	v_pk_mul_f32 v[2:3], v[2:3], v[186:187] op_sel_hi:[1,0]
	v_mul_f32_e32 v225, v225, v186
.Latt3_nr_20:
	v_sub_f32_e32 v82, v82, v223
	v_sub_f32_e32 v83, v83, v223
	v_sub_f32_e32 v84, v84, v223
	v_sub_f32_e32 v85, v85, v223
	v_exp_f32_e32 v82, v82
	v_exp_f32_e32 v83, v83
	v_exp_f32_e32 v84, v84
	v_exp_f32_e32 v85, v85
	v_sub_f32_e32 v86, v86, v223
	v_sub_f32_e32 v87, v87, v223
	v_sub_f32_e32 v88, v88, v223
	v_sub_f32_e32 v89, v89, v223
	v_exp_f32_e32 v86, v86
	v_exp_f32_e32 v87, v87
	v_exp_f32_e32 v88, v88
	v_exp_f32_e32 v89, v89
	v_cvt_pk_bf16_f32 v226, v82, v83
	v_cvt_pk_bf16_f32 v227, v84, v85
	v_cvt_pk_bf16_f32 v228, v86, v87
	v_cvt_pk_bf16_f32 v229, v88, v89
	s_nop 1
	v_mfma_f32_32x32x16_bf16 v[50:65], v[236:239], v[226:229], v[50:65]
	ds_read_b128 v[236:239], v205 offset:30240
	v_sub_f32_e32 v90, v90, v223
	v_sub_f32_e32 v91, v91, v223
	v_sub_f32_e32 v92, v92, v223
	v_sub_f32_e32 v93, v93, v223
	v_exp_f32_e32 v90, v90
	v_exp_f32_e32 v91, v91
	v_mfma_f32_32x32x16_bf16 v[34:49], v[240:243], v[226:229], v[34:49]
	ds_read_b128 v[240:243], v205 offset:34848
	v_exp_f32_e32 v92, v92
	v_exp_f32_e32 v93, v93
	v_sub_f32_e32 v94, v94, v223
	v_sub_f32_e32 v95, v95, v223
	v_sub_f32_e32 v96, v96, v223
	v_sub_f32_e32 v97, v97, v223
	v_mfma_f32_32x32x16_bf16 v[18:33], v[244:247], v[226:229], v[18:33]
	ds_read_b128 v[244:247], v205 offset:39456
	v_exp_f32_e32 v94, v94
	v_exp_f32_e32 v95, v95
	v_exp_f32_e32 v96, v96
	v_exp_f32_e32 v97, v97
	v_add_f32_e32 v186, 0, v82
	v_add_f32_e32 v186, v83, v186
	v_mfma_f32_32x32x16_bf16 v[2:17], v[248:251], v[226:229], v[2:17]
	ds_read_b128 v[248:251], v205 offset:25664
	v_add_f32_e32 v186, v84, v186
	v_add_f32_e32 v186, v85, v186
	v_add_f32_e32 v186, v86, v186
	v_add_f32_e32 v186, v87, v186
	v_add_f32_e32 v186, v88, v186
	v_add_f32_e32 v186, v89, v186
	v_cvt_pk_bf16_f32 v226, v90, v91
	v_cvt_pk_bf16_f32 v227, v92, v93
	v_cvt_pk_bf16_f32 v228, v94, v95
	v_cvt_pk_bf16_f32 v229, v96, v97
	s_nop 1
	v_mfma_f32_32x32x16_bf16 v[50:65], v[210:213], v[226:229], v[50:65]
	ds_read_b128 v[210:213], v205 offset:30272
	v_sub_f32_e32 v66, v66, v223
	v_sub_f32_e32 v67, v67, v223
	v_sub_f32_e32 v68, v68, v223
	v_sub_f32_e32 v69, v69, v223
	v_exp_f32_e32 v66, v66
	v_exp_f32_e32 v67, v67
	s_waitcnt lgkmcnt(4)
	v_mfma_f32_32x32x16_bf16 v[34:49], v[236:239], v[226:229], v[34:49]
	ds_read_b128 v[236:239], v205 offset:34880
	v_exp_f32_e32 v68, v68
	v_exp_f32_e32 v69, v69
	v_sub_f32_e32 v70, v70, v223
	v_sub_f32_e32 v71, v71, v223
	v_sub_f32_e32 v72, v72, v223
	v_sub_f32_e32 v73, v73, v223
	s_waitcnt lgkmcnt(4)
	v_mfma_f32_32x32x16_bf16 v[18:33], v[240:243], v[226:229], v[18:33]
	ds_read_b128 v[240:243], v205 offset:39488
	v_exp_f32_e32 v70, v70
	v_exp_f32_e32 v71, v71
	v_exp_f32_e32 v72, v72
	v_exp_f32_e32 v73, v73
	v_add_f32_e32 v186, v90, v186
	v_add_f32_e32 v186, v91, v186
	s_waitcnt lgkmcnt(4)
	v_mfma_f32_32x32x16_bf16 v[2:17], v[244:247], v[226:229], v[2:17]
	ds_read_b128 v[244:247], v205 offset:25696
	v_add_f32_e32 v186, v92, v186
	v_add_f32_e32 v186, v93, v186
	v_add_f32_e32 v186, v94, v186
	v_add_f32_e32 v186, v95, v186
	v_add_f32_e32 v186, v96, v186
	v_add_f32_e32 v186, v97, v186
	v_cvt_pk_bf16_f32 v226, v66, v67
	v_cvt_pk_bf16_f32 v227, v68, v69
	v_cvt_pk_bf16_f32 v228, v70, v71
	v_cvt_pk_bf16_f32 v229, v72, v73
	s_nop 1
	s_waitcnt lgkmcnt(4)
	v_mfma_f32_32x32x16_bf16 v[50:65], v[248:251], v[226:229], v[50:65]
	ds_read_b128 v[248:251], v205 offset:30304
	v_sub_f32_e32 v74, v74, v223
	v_sub_f32_e32 v75, v75, v223
	v_sub_f32_e32 v76, v76, v223
	v_sub_f32_e32 v77, v77, v223
	v_exp_f32_e32 v74, v74
	v_exp_f32_e32 v75, v75
	s_waitcnt lgkmcnt(4)
	v_mfma_f32_32x32x16_bf16 v[34:49], v[210:213], v[226:229], v[34:49]
	ds_read_b128 v[210:213], v205 offset:34912
	v_exp_f32_e32 v76, v76
	v_exp_f32_e32 v77, v77
	v_sub_f32_e32 v78, v78, v223
	v_sub_f32_e32 v79, v79, v223
	v_sub_f32_e32 v80, v80, v223
	v_sub_f32_e32 v81, v81, v223
	s_waitcnt lgkmcnt(4)
	v_mfma_f32_32x32x16_bf16 v[18:33], v[236:239], v[226:229], v[18:33]
	ds_read_b128 v[236:239], v205 offset:39520
	v_exp_f32_e32 v78, v78
	v_exp_f32_e32 v79, v79
	v_exp_f32_e32 v80, v80
	v_exp_f32_e32 v81, v81
	v_add_f32_e32 v186, v66, v186
	v_add_f32_e32 v186, v67, v186
	s_waitcnt lgkmcnt(4)
	v_mfma_f32_32x32x16_bf16 v[2:17], v[240:243], v[226:229], v[2:17]
	v_add_f32_e32 v186, v68, v186
	v_add_f32_e32 v186, v69, v186
	v_add_f32_e32 v186, v70, v186
	v_add_f32_e32 v186, v71, v186
	v_add_f32_e32 v186, v72, v186
	v_add_f32_e32 v186, v73, v186
	v_cvt_pk_bf16_f32 v226, v74, v75
	v_cvt_pk_bf16_f32 v227, v76, v77
	v_cvt_pk_bf16_f32 v228, v78, v79
	v_cvt_pk_bf16_f32 v229, v80, v81
	s_nop 1
	s_waitcnt lgkmcnt(3)
	v_mfma_f32_32x32x16_bf16 v[50:65], v[244:247], v[226:229], v[50:65]
	v_add_f32_e32 v186, v74, v186
	v_add_f32_e32 v186, v75, v186
	s_waitcnt lgkmcnt(2)
	v_mfma_f32_32x32x16_bf16 v[34:49], v[248:251], v[226:229], v[34:49]
	v_add_f32_e32 v186, v76, v186
	v_add_f32_e32 v186, v77, v186
	s_waitcnt lgkmcnt(1)
	v_mfma_f32_32x32x16_bf16 v[18:33], v[210:213], v[226:229], v[18:33]
	v_add_f32_e32 v186, v78, v186
	v_add_f32_e32 v186, v79, v186
	s_waitcnt lgkmcnt(0)
	v_mfma_f32_32x32x16_bf16 v[2:17], v[236:239], v[226:229], v[2:17]
	v_add_f32_e32 v186, v80, v186
	v_add_f32_e32 v186, v81, v186
	v_add_f32_e32 v224, v225, v186
	s_setprio 0
	s_add_i32 s13, s11, 2
	s_cmp_ge_u32 s13, s5
	s_cbranch_scc1 .Latt3_wskip_21
	v_add_u32_e32 v206, s72, v219
	v_add_u32_e32 v208, s72, v220
	v_add_u32_e32 v186, s72, v221
	v_add_u32_e32 v187, s72, v222
	s_add_i32 s13, s11, 3
	s_cmp_ge_u32 s13, s5
	s_cbranch_scc1 .Latt3_wtail_22
	s_waitcnt vmcnt(9)
	ds_write_b128 v206, v[102:105]
	s_waitcnt vmcnt(8)
	ds_write_b128 v208, v[106:109]
	s_waitcnt vmcnt(7)
	ds_write_b128 v186, v[114:117]
	s_waitcnt vmcnt(6)
	ds_write_b128 v187, v[98:101] offset:25600
	s_waitcnt vmcnt(5)
	ds_write_b128 v187, v[110:113] offset:34816
	s_branch .Latt3_wld_23

.Latt3_wdone_24:
.Latt3_wskip_21:
	s_mov_b32 s13, s70
	s_mov_b32 s70, s71
	s_mov_b32 s71, s72
	s_mov_b32 s72, s13
	s_add_i32 s11, s11, 1
	s_cmp_ge_u32 s11, s5
	s_cbranch_scc0 .Latt3_B_loop
.Latt3_exit:
	s_barrier
	s_branch .LBB0_40
